# scan chunk loop: ds_reads hoisted/renamed into free VGPRs in steps 2-5 + final, lgkmcnt waits recomputed; counted vmcnt in conv; DPP reductions
# speedup vs baseline: 1.0188x; 1.0088x over previous
.LBB0_340:
	s_cmp_eq_u32 s13, 0
	s_cselect_b64 s[94:95], -1, 0
	s_and_b64 s[94:95], s[88:89], s[94:95]
	s_and_saveexec_b64 vcc, s[94:95]
	s_xor_b64 s[94:95], exec, vcc
	s_cbranch_execz .LBB0_344
	v_mov_b32_e32 v73, 0
	s_and_b64 vcc, exec, s[2:3]
	v_mov_b32_e32 v72, 0
	v_mov_b32_e32 v75, 0
	v_mov_b32_e32 v74, 0
	v_mov_b32_e32 v77, 0
	v_mov_b32_e32 v76, 0
	s_cbranch_vccnz .LBB0_343
	global_load_dwordx2 v[72:73], v[162:163], off
	global_load_dwordx2 v[74:75], v[186:187], off
	global_load_dwordx2 v[76:77], v[188:189], off
	s_waitcnt vmcnt(0)
.LBB0_343:
.LBB0_344:
	s_andn2_saveexec_b64 s[94:95], s[94:95]
	s_cbranch_execz .LBB0_346
	s_waitcnt vmcnt(33)
	v_lshlrev_b32_e32 v72, 16, v250
	v_and_b32_e32 v73, 0xffff0000, v250
	v_lshlrev_b32_e32 v74, 16, v251
	v_and_b32_e32 v75, 0xffff0000, v251
	v_lshlrev_b32_e32 v76, 16, v252
	v_and_b32_e32 v77, 0xffff0000, v252
.LBB0_346:
	s_or_b64 exec, exec, s[94:95]
	s_waitcnt vmcnt(25)
	v_lshlrev_b32_e32 v78, 16, v249
	v_and_b32_e32 v79, 0xffff0000, v249
	v_pk_fma_f32 v[80:81], v[172:173], v[78:79], v[174:175]
	v_lshlrev_b32_e32 v88, 16, v247
	v_pk_fma_f32 v[80:81], v[170:171], v[76:77], v[80:81]
	v_and_b32_e32 v89, 0xffff0000, v247
	v_pk_fma_f32 v[80:81], v[168:169], v[74:75], v[80:81]
	v_lshlrev_b32_e32 v90, 16, v246
	v_pk_fma_f32 v[72:73], v[166:167], v[72:73], v[80:81]
	v_and_b32_e32 v91, 0xffff0000, v246
	v_pk_mul_f32 v[80:81], v[72:73], s[96:97] op_sel_hi:[1,0]
	v_lshlrev_b32_e32 v92, 16, v245
	v_exp_f32_e32 v80, v80
	v_exp_f32_e32 v81, v81
	v_and_b32_e32 v93, 0xffff0000, v245
	v_pk_add_f32 v[80:81], v[80:81], 1.0 op_sel_hi:[1,0]
	s_nop 0
	v_rcp_f32_e32 v80, v80
	v_rcp_f32_e32 v81, v81
	s_nop 0
	v_pk_mul_f32 v[72:73], v[72:73], v[80:81]
	v_lshlrev_b32_e32 v80, 16, v248
	v_and_b32_e32 v81, 0xffff0000, v248
	v_pk_fma_f32 v[82:83], v[172:173], v[80:81], v[174:175]
	s_nop 0
	v_pk_fma_f32 v[82:83], v[170:171], v[78:79], v[82:83]
	s_nop 0
	v_pk_fma_f32 v[82:83], v[168:169], v[76:77], v[82:83]
	s_nop 0
	v_pk_fma_f32 v[74:75], v[166:167], v[74:75], v[82:83]
	s_nop 0
	v_pk_mul_f32 v[82:83], v[74:75], s[96:97] op_sel_hi:[1,0]
	s_nop 0
	v_exp_f32_e32 v82, v82
	v_exp_f32_e32 v83, v83
	s_nop 0
	v_pk_add_f32 v[82:83], v[82:83], 1.0 op_sel_hi:[1,0]
	s_nop 0
	v_rcp_f32_e32 v82, v82
	v_rcp_f32_e32 v83, v83
	s_nop 0
	v_pk_mul_f32 v[74:75], v[74:75], v[82:83]
	v_pk_fma_f32 v[82:83], v[172:173], v[88:89], v[174:175]
	s_nop 0
	v_pk_fma_f32 v[82:83], v[170:171], v[80:81], v[82:83]
	s_nop 0
	v_pk_fma_f32 v[82:83], v[168:169], v[78:79], v[82:83]
	s_nop 0
	v_pk_fma_f32 v[76:77], v[166:167], v[76:77], v[82:83]
	s_nop 0
	v_pk_mul_f32 v[82:83], v[76:77], s[96:97] op_sel_hi:[1,0]
	s_nop 0
	v_exp_f32_e32 v82, v82
	v_exp_f32_e32 v83, v83
	s_nop 0
	v_pk_add_f32 v[82:83], v[82:83], 1.0 op_sel_hi:[1,0]
	s_nop 0
	v_rcp_f32_e32 v82, v82
	v_rcp_f32_e32 v83, v83
	s_nop 0
	v_pk_mul_f32 v[76:77], v[76:77], v[82:83]
	v_pk_fma_f32 v[82:83], v[172:173], v[90:91], v[174:175]
	s_nop 0
	v_pk_fma_f32 v[82:83], v[170:171], v[88:89], v[82:83]
	s_nop 0
	v_pk_fma_f32 v[82:83], v[168:169], v[80:81], v[82:83]
	s_nop 0
	v_pk_fma_f32 v[78:79], v[166:167], v[78:79], v[82:83]
	s_nop 0
	v_pk_mul_f32 v[82:83], v[78:79], s[96:97] op_sel_hi:[1,0]
	s_nop 0
	v_exp_f32_e32 v82, v82
	v_exp_f32_e32 v83, v83
	s_nop 0
	v_pk_add_f32 v[82:83], v[82:83], 1.0 op_sel_hi:[1,0]
	s_nop 0
	v_rcp_f32_e32 v82, v82
	v_rcp_f32_e32 v83, v83
	s_nop 0
	v_pk_mul_f32 v[84:85], v[78:79], v[82:83]
	v_pk_fma_f32 v[78:79], v[172:173], v[92:93], v[174:175]
	v_lshlrev_b32_e32 v82, 16, v244
	v_pk_fma_f32 v[78:79], v[170:171], v[90:91], v[78:79]
	v_and_b32_e32 v83, 0xffff0000, v244
	v_pk_fma_f32 v[78:79], v[168:169], v[88:89], v[78:79]
	s_nop 0
	v_pk_fma_f32 v[78:79], v[166:167], v[80:81], v[78:79]
	s_nop 0
	v_pk_mul_f32 v[80:81], v[78:79], s[96:97] op_sel_hi:[1,0]
	s_nop 0
	v_exp_f32_e32 v80, v80
	v_exp_f32_e32 v81, v81
	s_nop 0
	v_pk_add_f32 v[80:81], v[80:81], 1.0 op_sel_hi:[1,0]
	s_nop 0
	v_rcp_f32_e32 v80, v80
	v_rcp_f32_e32 v81, v81
	s_nop 0
	v_pk_mul_f32 v[86:87], v[78:79], v[80:81]
	v_pk_fma_f32 v[78:79], v[172:173], v[82:83], v[174:175]
	s_nop 0
	v_pk_fma_f32 v[78:79], v[170:171], v[92:93], v[78:79]
	s_nop 0
	v_pk_fma_f32 v[78:79], v[168:169], v[90:91], v[78:79]
	s_nop 0
	v_pk_fma_f32 v[78:79], v[166:167], v[88:89], v[78:79]
	s_nop 0
	v_pk_mul_f32 v[80:81], v[78:79], s[96:97] op_sel_hi:[1,0]
	s_nop 0
	v_exp_f32_e32 v80, v80
	v_exp_f32_e32 v81, v81
	s_nop 0
	v_pk_add_f32 v[80:81], v[80:81], 1.0 op_sel_hi:[1,0]
	s_nop 0
	v_rcp_f32_e32 v80, v80
	v_rcp_f32_e32 v81, v81
	s_nop 0
	v_pk_mul_f32 v[88:89], v[78:79], v[80:81]
	v_lshlrev_b32_e32 v80, 16, v243
	v_and_b32_e32 v81, 0xffff0000, v243
	v_pk_fma_f32 v[78:79], v[172:173], v[80:81], v[174:175]
	s_nop 0
	v_pk_fma_f32 v[78:79], v[170:171], v[82:83], v[78:79]
	s_nop 0
	v_pk_fma_f32 v[78:79], v[168:169], v[92:93], v[78:79]
	s_nop 0
	v_pk_fma_f32 v[78:79], v[166:167], v[90:91], v[78:79]
	s_nop 0
	v_pk_mul_f32 v[90:91], v[78:79], s[96:97] op_sel_hi:[1,0]
	s_nop 0
	v_exp_f32_e32 v90, v90
	v_exp_f32_e32 v91, v91
	s_nop 0
	v_pk_add_f32 v[90:91], v[90:91], 1.0 op_sel_hi:[1,0]
	s_nop 0
	v_rcp_f32_e32 v90, v90
	v_rcp_f32_e32 v91, v91
	s_nop 0
	v_pk_mul_f32 v[90:91], v[78:79], v[90:91]
	v_lshlrev_b32_e32 v78, 16, v242
	v_and_b32_e32 v79, 0xffff0000, v242
	v_pk_fma_f32 v[110:111], v[172:173], v[78:79], v[174:175]
	s_nop 0
	v_pk_fma_f32 v[110:111], v[170:171], v[80:81], v[110:111]
	s_nop 0
	v_pk_fma_f32 v[110:111], v[168:169], v[82:83], v[110:111]
	s_nop 0
	v_pk_fma_f32 v[92:93], v[166:167], v[92:93], v[110:111]
	s_nop 0
	v_pk_mul_f32 v[110:111], v[92:93], s[96:97] op_sel_hi:[1,0]
	s_nop 0
	v_exp_f32_e32 v110, v110
	v_exp_f32_e32 v111, v111
	s_nop 0
	v_pk_add_f32 v[110:111], v[110:111], 1.0 op_sel_hi:[1,0]
	s_nop 0
	v_rcp_f32_e32 v110, v110
	v_rcp_f32_e32 v111, v111
	s_nop 0
	v_pk_mul_f32 v[92:93], v[92:93], v[110:111]
	s_and_saveexec_b64 s[16:17], s[4:5]
	s_xor_b64 s[94:95], exec, s[16:17]
	s_cbranch_execz .LBB0_354
	s_and_saveexec_b64 s[16:17], s[8:9]
	s_xor_b64 vcc, exec, s[16:17]
	s_cbranch_execz .LBB0_351
	v_cvt_pk_bf16_f32 v72, v72, v73
	ds_write_b32 v213, v72
	v_cvt_pk_bf16_f32 v72, v74, v75
	ds_write_b32 v214, v72
	v_cvt_pk_bf16_f32 v72, v76, v77
	ds_write_b32 v215, v72
	v_cvt_pk_bf16_f32 v72, v84, v85
	ds_write_b32 v212, v72 offset:48
	v_cvt_pk_bf16_f32 v72, v86, v87
	ds_write_b32 v212, v72 offset:320
	v_cvt_pk_bf16_f32 v72, v88, v89
	ds_write_b32 v212, v72 offset:592
	v_cvt_pk_bf16_f32 v72, v90, v91
	ds_write_b32 v212, v72 offset:864
	v_cvt_pk_bf16_f32 v72, v92, v93
	ds_write_b32 v212, v72 offset:1136

.LBB0_356:
	s_or_b64 exec, exec, s[94:95]
	s_waitcnt vmcnt(16)
	v_lshlrev_b32_e32 v84, 16, v241
	v_and_b32_e32 v85, 0xffff0000, v241
	v_pk_fma_f32 v[72:73], v[172:173], v[84:85], v[174:175]
	v_lshlrev_b32_e32 v92, 16, v237
	v_pk_fma_f32 v[72:73], v[170:171], v[78:79], v[72:73]
	v_and_b32_e32 v93, 0xffff0000, v237
	v_pk_fma_f32 v[72:73], v[168:169], v[80:81], v[72:73]
	s_nop 0
	v_pk_fma_f32 v[72:73], v[166:167], v[82:83], v[72:73]
	v_lshlrev_b32_e32 v82, 16, v240
	v_pk_mul_f32 v[74:75], v[72:73], s[96:97] op_sel_hi:[1,0]
	v_and_b32_e32 v83, 0xffff0000, v240
	v_exp_f32_e32 v74, v74
	v_exp_f32_e32 v75, v75
	s_nop 0
	v_pk_add_f32 v[74:75], v[74:75], 1.0 op_sel_hi:[1,0]
	s_nop 0
	v_rcp_f32_e32 v74, v74
	v_rcp_f32_e32 v75, v75
	s_nop 0
	v_pk_mul_f32 v[72:73], v[72:73], v[74:75]
	v_pk_fma_f32 v[74:75], v[172:173], v[82:83], v[174:175]
	s_nop 0
	v_pk_fma_f32 v[74:75], v[170:171], v[84:85], v[74:75]
	s_nop 0
	v_pk_fma_f32 v[74:75], v[168:169], v[78:79], v[74:75]
	s_nop 0
	v_pk_fma_f32 v[74:75], v[166:167], v[80:81], v[74:75]
	v_lshlrev_b32_e32 v80, 16, v239
	v_pk_mul_f32 v[76:77], v[74:75], s[96:97] op_sel_hi:[1,0]
	v_and_b32_e32 v81, 0xffff0000, v239
	v_exp_f32_e32 v76, v76
	v_exp_f32_e32 v77, v77
	s_nop 0
	v_pk_add_f32 v[76:77], v[76:77], 1.0 op_sel_hi:[1,0]
	s_nop 0
	v_rcp_f32_e32 v76, v76
	v_rcp_f32_e32 v77, v77
	s_nop 0
	v_pk_mul_f32 v[74:75], v[74:75], v[76:77]
	v_pk_fma_f32 v[76:77], v[172:173], v[80:81], v[174:175]
	s_nop 0
	v_pk_fma_f32 v[76:77], v[170:171], v[82:83], v[76:77]
	s_nop 0
	v_pk_fma_f32 v[76:77], v[168:169], v[84:85], v[76:77]
	s_nop 0
	v_pk_fma_f32 v[76:77], v[166:167], v[78:79], v[76:77]
	s_nop 0
	v_pk_mul_f32 v[78:79], v[76:77], s[96:97] op_sel_hi:[1,0]
	s_nop 0
	v_exp_f32_e32 v78, v78
	v_exp_f32_e32 v79, v79
	s_nop 0
	v_pk_add_f32 v[78:79], v[78:79], 1.0 op_sel_hi:[1,0]
	s_nop 0
	v_rcp_f32_e32 v78, v78
	v_rcp_f32_e32 v79, v79
	s_nop 0
	v_pk_mul_f32 v[76:77], v[76:77], v[78:79]
	v_lshlrev_b32_e32 v78, 16, v238
	v_and_b32_e32 v79, 0xffff0000, v238
	v_pk_fma_f32 v[86:87], v[172:173], v[78:79], v[174:175]
	s_nop 0
	v_pk_fma_f32 v[86:87], v[170:171], v[80:81], v[86:87]
	s_nop 0
	v_pk_fma_f32 v[86:87], v[168:169], v[82:83], v[86:87]
	s_nop 0
	v_pk_fma_f32 v[84:85], v[166:167], v[84:85], v[86:87]
	s_nop 0
	v_pk_mul_f32 v[86:87], v[84:85], s[96:97] op_sel_hi:[1,0]
	s_nop 0
	v_exp_f32_e32 v86, v86
	v_exp_f32_e32 v87, v87
	s_nop 0
	v_pk_add_f32 v[86:87], v[86:87], 1.0 op_sel_hi:[1,0]
	s_nop 0
	v_rcp_f32_e32 v86, v86
	v_rcp_f32_e32 v87, v87
	s_nop 0
	v_pk_mul_f32 v[84:85], v[84:85], v[86:87]
	v_pk_fma_f32 v[86:87], v[172:173], v[92:93], v[174:175]
	s_nop 0
	v_pk_fma_f32 v[86:87], v[170:171], v[78:79], v[86:87]
	s_nop 0
	v_pk_fma_f32 v[86:87], v[168:169], v[80:81], v[86:87]
	s_nop 0
	v_pk_fma_f32 v[82:83], v[166:167], v[82:83], v[86:87]
	s_nop 0
	v_pk_mul_f32 v[86:87], v[82:83], s[96:97] op_sel_hi:[1,0]
	s_nop 0
	v_exp_f32_e32 v86, v86
	v_exp_f32_e32 v87, v87
	s_nop 0
	v_pk_add_f32 v[86:87], v[86:87], 1.0 op_sel_hi:[1,0]
	s_nop 0
	v_rcp_f32_e32 v86, v86
	v_rcp_f32_e32 v87, v87
	s_nop 0
	v_pk_mul_f32 v[86:87], v[82:83], v[86:87]
	v_lshlrev_b32_e32 v82, 16, v236
	v_and_b32_e32 v83, 0xffff0000, v236
	v_pk_fma_f32 v[88:89], v[172:173], v[82:83], v[174:175]
	s_nop 0
	v_pk_fma_f32 v[88:89], v[170:171], v[92:93], v[88:89]
	s_nop 0
	v_pk_fma_f32 v[88:89], v[168:169], v[78:79], v[88:89]
	s_nop 0
	v_pk_fma_f32 v[80:81], v[166:167], v[80:81], v[88:89]
	s_nop 0
	v_pk_mul_f32 v[88:89], v[80:81], s[96:97] op_sel_hi:[1,0]
	s_nop 0
	v_exp_f32_e32 v88, v88
	v_exp_f32_e32 v89, v89
	s_nop 0
	v_pk_add_f32 v[88:89], v[88:89], 1.0 op_sel_hi:[1,0]
	s_nop 0
	v_rcp_f32_e32 v88, v88
	v_rcp_f32_e32 v89, v89
	s_nop 0
	v_pk_mul_f32 v[88:89], v[80:81], v[88:89]
	v_lshlrev_b32_e32 v80, 16, v108
	v_and_b32_e32 v81, 0xffff0000, v108
	v_pk_fma_f32 v[90:91], v[172:173], v[80:81], v[174:175]
	s_nop 0
	v_pk_fma_f32 v[90:91], v[170:171], v[82:83], v[90:91]
	s_nop 0
	v_pk_fma_f32 v[90:91], v[168:169], v[92:93], v[90:91]
	s_nop 0
	v_pk_fma_f32 v[78:79], v[166:167], v[78:79], v[90:91]
	s_nop 0
	v_pk_mul_f32 v[90:91], v[78:79], s[96:97] op_sel_hi:[1,0]
	s_nop 0
	v_exp_f32_e32 v90, v90
	v_exp_f32_e32 v91, v91
	s_nop 0
	v_pk_add_f32 v[90:91], v[90:91], 1.0 op_sel_hi:[1,0]
	s_nop 0
	v_rcp_f32_e32 v90, v90
	v_rcp_f32_e32 v91, v91
	s_nop 0
	v_pk_mul_f32 v[90:91], v[78:79], v[90:91]
	v_lshlrev_b32_e32 v78, 16, v107
	v_and_b32_e32 v79, 0xffff0000, v107
	v_pk_fma_f32 v[108:109], v[172:173], v[78:79], v[174:175]
	s_nop 0
	v_pk_fma_f32 v[108:109], v[170:171], v[80:81], v[108:109]
	s_nop 0
	v_pk_fma_f32 v[108:109], v[168:169], v[82:83], v[108:109]
	s_nop 0
	v_pk_fma_f32 v[92:93], v[166:167], v[92:93], v[108:109]
	s_nop 0
	v_pk_mul_f32 v[108:109], v[92:93], s[96:97] op_sel_hi:[1,0]
	s_nop 0
	v_exp_f32_e32 v108, v108
	v_exp_f32_e32 v109, v109
	s_nop 0
	v_pk_add_f32 v[108:109], v[108:109], 1.0 op_sel_hi:[1,0]
	s_nop 0
	v_rcp_f32_e32 v108, v108
	v_rcp_f32_e32 v109, v109
	s_nop 0
	v_pk_mul_f32 v[92:93], v[92:93], v[108:109]
	s_and_saveexec_b64 s[16:17], s[4:5]
	s_xor_b64 s[94:95], exec, s[16:17]
	s_cbranch_execz .LBB0_362
	s_and_saveexec_b64 s[16:17], s[8:9]
	s_xor_b64 vcc, exec, s[16:17]
	s_cbranch_execz .LBB0_359
	v_cvt_pk_bf16_f32 v72, v72, v73
	ds_write_b32 v220, v72
	v_cvt_pk_bf16_f32 v72, v74, v75
	ds_write_b32 v212, v72 offset:1680
	v_cvt_pk_bf16_f32 v72, v76, v77
	ds_write_b32 v212, v72 offset:1952
	v_cvt_pk_bf16_f32 v72, v84, v85
	ds_write_b32 v212, v72 offset:2224
	v_cvt_pk_bf16_f32 v72, v86, v87
	ds_write_b32 v212, v72 offset:2496
	v_cvt_pk_bf16_f32 v72, v88, v89
	ds_write_b32 v212, v72 offset:2768
	v_cvt_pk_bf16_f32 v72, v90, v91
	ds_write_b32 v212, v72 offset:3040
	v_cvt_pk_bf16_f32 v72, v92, v93
	ds_write_b32 v212, v72 offset:3312

.LBB0_364:
	s_or_b64 exec, exec, s[94:95]
	s_waitcnt vmcnt(8)
	v_lshlrev_b32_e32 v84, 16, v106
	v_and_b32_e32 v85, 0xffff0000, v106
	v_pk_fma_f32 v[72:73], v[172:173], v[84:85], v[174:175]
	v_lshlrev_b32_e32 v92, 16, v102
	v_pk_fma_f32 v[72:73], v[170:171], v[78:79], v[72:73]
	v_and_b32_e32 v93, 0xffff0000, v102
	v_pk_fma_f32 v[72:73], v[168:169], v[80:81], v[72:73]
	s_nop 0
	v_pk_fma_f32 v[72:73], v[166:167], v[82:83], v[72:73]
	v_lshlrev_b32_e32 v82, 16, v105
	v_pk_mul_f32 v[74:75], v[72:73], s[96:97] op_sel_hi:[1,0]
	v_and_b32_e32 v83, 0xffff0000, v105
	v_exp_f32_e32 v74, v74
	v_exp_f32_e32 v75, v75
	s_nop 0
	v_pk_add_f32 v[74:75], v[74:75], 1.0 op_sel_hi:[1,0]
	s_nop 0
	v_rcp_f32_e32 v74, v74
	v_rcp_f32_e32 v75, v75
	s_nop 0
	v_pk_mul_f32 v[72:73], v[72:73], v[74:75]
	v_pk_fma_f32 v[74:75], v[172:173], v[82:83], v[174:175]
	s_nop 0
	v_pk_fma_f32 v[74:75], v[170:171], v[84:85], v[74:75]
	s_nop 0
	v_pk_fma_f32 v[74:75], v[168:169], v[78:79], v[74:75]
	s_nop 0
	v_pk_fma_f32 v[74:75], v[166:167], v[80:81], v[74:75]
	v_lshlrev_b32_e32 v80, 16, v104
	v_pk_mul_f32 v[76:77], v[74:75], s[96:97] op_sel_hi:[1,0]
	v_and_b32_e32 v81, 0xffff0000, v104
	v_exp_f32_e32 v76, v76
	v_exp_f32_e32 v77, v77
	s_nop 0
	v_pk_add_f32 v[76:77], v[76:77], 1.0 op_sel_hi:[1,0]
	s_nop 0
	v_rcp_f32_e32 v76, v76
	v_rcp_f32_e32 v77, v77
	s_nop 0
	v_pk_mul_f32 v[74:75], v[74:75], v[76:77]
	v_pk_fma_f32 v[76:77], v[172:173], v[80:81], v[174:175]
	s_nop 0
	v_pk_fma_f32 v[76:77], v[170:171], v[82:83], v[76:77]
	s_nop 0
	v_pk_fma_f32 v[76:77], v[168:169], v[84:85], v[76:77]
	s_nop 0
	v_pk_fma_f32 v[76:77], v[166:167], v[78:79], v[76:77]
	s_nop 0
	v_pk_mul_f32 v[78:79], v[76:77], s[96:97] op_sel_hi:[1,0]
	s_nop 0
	v_exp_f32_e32 v78, v78
	v_exp_f32_e32 v79, v79
	s_nop 0
	v_pk_add_f32 v[78:79], v[78:79], 1.0 op_sel_hi:[1,0]
	s_nop 0
	v_rcp_f32_e32 v78, v78
	v_rcp_f32_e32 v79, v79
	s_nop 0
	v_pk_mul_f32 v[76:77], v[76:77], v[78:79]
	v_lshlrev_b32_e32 v78, 16, v103
	v_and_b32_e32 v79, 0xffff0000, v103
	v_pk_fma_f32 v[86:87], v[172:173], v[78:79], v[174:175]
	s_nop 0
	v_pk_fma_f32 v[86:87], v[170:171], v[80:81], v[86:87]
	s_nop 0
	v_pk_fma_f32 v[86:87], v[168:169], v[82:83], v[86:87]
	s_nop 0
	v_pk_fma_f32 v[84:85], v[166:167], v[84:85], v[86:87]
	s_nop 0
	v_pk_mul_f32 v[86:87], v[84:85], s[96:97] op_sel_hi:[1,0]
	s_nop 0
	v_exp_f32_e32 v86, v86
	v_exp_f32_e32 v87, v87
	s_nop 0
	v_pk_add_f32 v[86:87], v[86:87], 1.0 op_sel_hi:[1,0]
	s_nop 0
	v_rcp_f32_e32 v86, v86
	v_rcp_f32_e32 v87, v87
	s_nop 0
	v_pk_mul_f32 v[84:85], v[84:85], v[86:87]
	v_pk_fma_f32 v[86:87], v[172:173], v[92:93], v[174:175]
	s_nop 0
	v_pk_fma_f32 v[86:87], v[170:171], v[78:79], v[86:87]
	s_nop 0
	v_pk_fma_f32 v[86:87], v[168:169], v[80:81], v[86:87]
	s_nop 0
	v_pk_fma_f32 v[82:83], v[166:167], v[82:83], v[86:87]
	s_nop 0
	v_pk_mul_f32 v[86:87], v[82:83], s[96:97] op_sel_hi:[1,0]
	s_nop 0
	v_exp_f32_e32 v86, v86
	v_exp_f32_e32 v87, v87
	s_nop 0
	v_pk_add_f32 v[86:87], v[86:87], 1.0 op_sel_hi:[1,0]
	s_nop 0
	v_rcp_f32_e32 v86, v86
	v_rcp_f32_e32 v87, v87
	s_nop 0
	v_pk_mul_f32 v[86:87], v[82:83], v[86:87]
	v_lshlrev_b32_e32 v82, 16, v101
	v_and_b32_e32 v83, 0xffff0000, v101
	v_pk_fma_f32 v[88:89], v[172:173], v[82:83], v[174:175]
	s_nop 0
	v_pk_fma_f32 v[88:89], v[170:171], v[92:93], v[88:89]
	s_nop 0
	v_pk_fma_f32 v[88:89], v[168:169], v[78:79], v[88:89]
	s_nop 0
	v_pk_fma_f32 v[80:81], v[166:167], v[80:81], v[88:89]
	s_nop 0
	v_pk_mul_f32 v[88:89], v[80:81], s[96:97] op_sel_hi:[1,0]
	s_nop 0
	v_exp_f32_e32 v88, v88
	v_exp_f32_e32 v89, v89
	s_nop 0
	v_pk_add_f32 v[88:89], v[88:89], 1.0 op_sel_hi:[1,0]
	s_nop 0
	v_rcp_f32_e32 v88, v88
	v_rcp_f32_e32 v89, v89
	s_nop 0
	v_pk_mul_f32 v[88:89], v[80:81], v[88:89]
	v_lshlrev_b32_e32 v80, 16, v100
	v_and_b32_e32 v81, 0xffff0000, v100
	v_pk_fma_f32 v[90:91], v[172:173], v[80:81], v[174:175]
	s_nop 0
	v_pk_fma_f32 v[90:91], v[170:171], v[82:83], v[90:91]
	s_nop 0
	v_pk_fma_f32 v[90:91], v[168:169], v[92:93], v[90:91]
	s_nop 0
	v_pk_fma_f32 v[78:79], v[166:167], v[78:79], v[90:91]
	s_nop 0
	v_pk_mul_f32 v[90:91], v[78:79], s[96:97] op_sel_hi:[1,0]
	s_nop 0
	v_exp_f32_e32 v90, v90
	v_exp_f32_e32 v91, v91
	s_nop 0
	v_pk_add_f32 v[90:91], v[90:91], 1.0 op_sel_hi:[1,0]
	s_nop 0
	v_rcp_f32_e32 v90, v90
	v_rcp_f32_e32 v91, v91
	s_nop 0
	v_pk_mul_f32 v[90:91], v[78:79], v[90:91]
	v_lshlrev_b32_e32 v78, 16, v99
	v_and_b32_e32 v79, 0xffff0000, v99
	v_pk_fma_f32 v[100:101], v[172:173], v[78:79], v[174:175]
	s_nop 0
	v_pk_fma_f32 v[100:101], v[170:171], v[80:81], v[100:101]
	s_nop 0
	v_pk_fma_f32 v[100:101], v[168:169], v[82:83], v[100:101]
	s_nop 0
	v_pk_fma_f32 v[92:93], v[166:167], v[92:93], v[100:101]
	s_nop 0
	v_pk_mul_f32 v[100:101], v[92:93], s[96:97] op_sel_hi:[1,0]
	s_nop 0
	v_exp_f32_e32 v100, v100
	v_exp_f32_e32 v101, v101
	s_nop 0
	v_pk_add_f32 v[100:101], v[100:101], 1.0 op_sel_hi:[1,0]
	s_nop 0
	v_rcp_f32_e32 v100, v100
	v_rcp_f32_e32 v101, v101
	s_nop 0
	v_pk_mul_f32 v[92:93], v[92:93], v[100:101]
	s_and_saveexec_b64 s[16:17], s[4:5]
	s_xor_b64 s[94:95], exec, s[16:17]
	s_cbranch_execz .LBB0_370
	s_and_saveexec_b64 s[16:17], s[8:9]
	s_xor_b64 vcc, exec, s[16:17]
	s_cbranch_execz .LBB0_367
	v_cvt_pk_bf16_f32 v72, v72, v73
	v_add_u32_e32 v73, v205, v219
	ds_write_b32 v73, v72 offset:1408
	v_cvt_pk_bf16_f32 v72, v74, v75
	ds_write_b32 v212, v72 offset:3856
	v_cvt_pk_bf16_f32 v72, v76, v77
	ds_write_b32 v212, v72 offset:4128
	v_cvt_pk_bf16_f32 v72, v84, v85
	ds_write_b32 v212, v72 offset:4400
	v_cvt_pk_bf16_f32 v72, v86, v87
	ds_write_b32 v212, v72 offset:4672
	v_cvt_pk_bf16_f32 v72, v88, v89
	ds_write_b32 v212, v72 offset:4944
	v_cvt_pk_bf16_f32 v72, v90, v91
	ds_write_b32 v212, v72 offset:5216
	v_cvt_pk_bf16_f32 v72, v92, v93
	ds_write_b32 v212, v72 offset:5488

.LBB0_370:
	s_andn2_saveexec_b64 s[94:95], s[94:95]
	s_cbranch_execz .LBB0_372
	v_cvt_pk_bf16_f32 v100, v72, v74
	v_cvt_pk_bf16_f32 v101, v76, v84
	v_cvt_pk_bf16_f32 v102, v86, v88
	v_cvt_pk_bf16_f32 v103, v90, v92
	ds_write_b128 v218, v[100:103] offset:53280
	v_cvt_pk_bf16_f32 v72, v73, v75
	v_cvt_pk_bf16_f32 v73, v77, v85
	v_cvt_pk_bf16_f32 v74, v87, v89
	v_cvt_pk_bf16_f32 v75, v91, v93
	ds_write_b128 v218, v[72:75] offset:53424
.LBB0_372:
	s_or_b64 exec, exec, s[94:95]
	s_cmp_eq_u32 s15, s1
	s_cselect_b64 s[16:17], -1, 0
	s_and_b64 s[16:17], s[6:7], s[16:17]
	s_waitcnt vmcnt(2)
	v_lshlrev_b32_e32 v2, 16, v3
	v_and_b32_e32 v3, 0xffff0000, v3
	s_waitcnt vmcnt(1)
	v_lshlrev_b32_e32 v68, 16, v69
	v_and_b32_e32 v69, 0xffff0000, v69
	s_waitcnt vmcnt(0)
	v_lshlrev_b32_e32 v70, 16, v71
	v_and_b32_e32 v71, 0xffff0000, v71
	s_and_saveexec_b64 s[94:95], s[16:17]
	s_cbranch_execz .LBB0_348
	global_store_dwordx2 v[160:161], v[2:3], off
	global_store_dwordx2 v[182:183], v[68:69], off
	global_store_dwordx2 v[184:185], v[70:71], off
.LBB0_348:
	s_or_b64 exec, exec, s[94:95]
	v_lshlrev_b32_e32 v84, 16, v98
	v_and_b32_e32 v85, 0xffff0000, v98
	v_pk_fma_f32 v[72:73], v[172:173], v[84:85], v[174:175]
	v_lshlrev_b32_e32 v86, 16, v96
	v_pk_fma_f32 v[72:73], v[170:171], v[78:79], v[72:73]
	v_and_b32_e32 v87, 0xffff0000, v96
	v_pk_fma_f32 v[72:73], v[168:169], v[80:81], v[72:73]
	v_lshlrev_b32_e32 v88, 16, v95
	v_pk_fma_f32 v[72:73], v[166:167], v[82:83], v[72:73]
	v_lshlrev_b32_e32 v82, 16, v97
	v_pk_mul_f32 v[74:75], v[72:73], s[96:97] op_sel_hi:[1,0]
	v_and_b32_e32 v83, 0xffff0000, v97
	v_exp_f32_e32 v74, v74
	v_exp_f32_e32 v75, v75
	v_and_b32_e32 v89, 0xffff0000, v95
	v_lshlrev_b32_e32 v90, 16, v94
	v_and_b32_e32 v91, 0xffff0000, v94
	v_pk_add_f32 v[74:75], v[74:75], 1.0 op_sel_hi:[1,0]
	v_pk_fma_f32 v[70:71], v[172:173], v[70:71], v[174:175]
	v_rcp_f32_e32 v74, v74
	v_rcp_f32_e32 v75, v75
	s_nop 0
	v_pk_mul_f32 v[72:73], v[72:73], v[74:75]
	v_pk_fma_f32 v[74:75], v[172:173], v[82:83], v[174:175]
	s_nop 0
	v_pk_fma_f32 v[74:75], v[170:171], v[84:85], v[74:75]
	s_nop 0
	v_pk_fma_f32 v[74:75], v[168:169], v[78:79], v[74:75]
	s_nop 0
	v_pk_fma_f32 v[74:75], v[166:167], v[80:81], v[74:75]
	s_nop 0
	v_pk_mul_f32 v[76:77], v[74:75], s[96:97] op_sel_hi:[1,0]
	s_nop 0
	v_exp_f32_e32 v76, v76
	v_exp_f32_e32 v77, v77
	s_nop 0
	v_pk_add_f32 v[76:77], v[76:77], 1.0 op_sel_hi:[1,0]
	s_nop 0
	v_rcp_f32_e32 v76, v76
	v_rcp_f32_e32 v77, v77
	s_nop 0
	v_pk_mul_f32 v[74:75], v[74:75], v[76:77]
	v_pk_fma_f32 v[76:77], v[172:173], v[86:87], v[174:175]
	s_nop 0
	v_pk_fma_f32 v[76:77], v[170:171], v[82:83], v[76:77]
	s_nop 0
	v_pk_fma_f32 v[76:77], v[168:169], v[84:85], v[76:77]
	s_nop 0
	v_pk_fma_f32 v[76:77], v[166:167], v[78:79], v[76:77]
	s_nop 0
	v_pk_mul_f32 v[78:79], v[76:77], s[96:97] op_sel_hi:[1,0]
	s_nop 0
	v_exp_f32_e32 v78, v78
	v_exp_f32_e32 v79, v79
	s_nop 0
	v_pk_add_f32 v[78:79], v[78:79], 1.0 op_sel_hi:[1,0]
	s_nop 0
	v_rcp_f32_e32 v78, v78
	v_rcp_f32_e32 v79, v79
	s_nop 0
	v_pk_mul_f32 v[76:77], v[76:77], v[78:79]
	v_pk_fma_f32 v[78:79], v[172:173], v[88:89], v[174:175]
	s_nop 0
	v_pk_fma_f32 v[78:79], v[170:171], v[86:87], v[78:79]
	s_nop 0
	v_pk_fma_f32 v[78:79], v[168:169], v[82:83], v[78:79]
	s_nop 0
	v_pk_fma_f32 v[78:79], v[166:167], v[84:85], v[78:79]
	s_nop 0
	v_pk_mul_f32 v[80:81], v[78:79], s[96:97] op_sel_hi:[1,0]
	s_nop 0
	v_exp_f32_e32 v80, v80
	v_exp_f32_e32 v81, v81
	s_nop 0
	v_pk_add_f32 v[80:81], v[80:81], 1.0 op_sel_hi:[1,0]
	s_nop 0
	v_rcp_f32_e32 v80, v80
	v_rcp_f32_e32 v81, v81
	s_nop 0
	v_pk_mul_f32 v[78:79], v[78:79], v[80:81]
	v_pk_fma_f32 v[80:81], v[172:173], v[90:91], v[174:175]
	s_nop 0
	v_pk_fma_f32 v[80:81], v[170:171], v[88:89], v[80:81]
	s_nop 0
	v_pk_fma_f32 v[80:81], v[168:169], v[86:87], v[80:81]
	s_nop 0
	v_pk_fma_f32 v[80:81], v[166:167], v[82:83], v[80:81]
	s_nop 0
	v_pk_mul_f32 v[82:83], v[80:81], s[96:97] op_sel_hi:[1,0]
	s_nop 0
	v_exp_f32_e32 v82, v82
	v_exp_f32_e32 v83, v83
	s_nop 0
	v_pk_add_f32 v[82:83], v[82:83], 1.0 op_sel_hi:[1,0]
	s_nop 0
	v_rcp_f32_e32 v82, v82
	v_rcp_f32_e32 v83, v83
	s_nop 0
	v_pk_mul_f32 v[80:81], v[80:81], v[82:83]
	v_pk_fma_f32 v[82:83], v[172:173], v[2:3], v[174:175]
	s_nop 0
	v_pk_fma_f32 v[82:83], v[170:171], v[90:91], v[82:83]
	s_nop 0
	v_pk_fma_f32 v[82:83], v[168:169], v[88:89], v[82:83]
	s_nop 0
	v_pk_fma_f32 v[82:83], v[166:167], v[86:87], v[82:83]
	s_nop 0
	v_pk_mul_f32 v[84:85], v[82:83], s[96:97] op_sel_hi:[1,0]
	s_nop 0
	v_exp_f32_e32 v84, v84
	v_exp_f32_e32 v85, v85
	s_nop 0
	v_pk_add_f32 v[84:85], v[84:85], 1.0 op_sel_hi:[1,0]
	s_nop 0
	v_rcp_f32_e32 v84, v84
	v_rcp_f32_e32 v85, v85
	s_nop 0
	v_pk_mul_f32 v[82:83], v[82:83], v[84:85]
	v_pk_fma_f32 v[84:85], v[172:173], v[68:69], v[174:175]
	v_pk_fma_f32 v[68:69], v[170:171], v[68:69], v[70:71]
	v_pk_fma_f32 v[84:85], v[170:171], v[2:3], v[84:85]
	v_pk_fma_f32 v[2:3], v[168:169], v[2:3], v[68:69]
	v_pk_fma_f32 v[84:85], v[168:169], v[90:91], v[84:85]
	v_pk_fma_f32 v[2:3], v[166:167], v[90:91], v[2:3]
	v_pk_fma_f32 v[84:85], v[166:167], v[88:89], v[84:85]
	v_pk_mul_f32 v[68:69], v[2:3], s[96:97] op_sel_hi:[1,0]
	v_pk_mul_f32 v[86:87], v[84:85], s[96:97] op_sel_hi:[1,0]
	v_exp_f32_e32 v68, v68
	v_exp_f32_e32 v86, v86
	v_exp_f32_e32 v87, v87
	v_exp_f32_e32 v69, v69
	v_pk_add_f32 v[86:87], v[86:87], 1.0 op_sel_hi:[1,0]
	v_pk_add_f32 v[68:69], v[68:69], 1.0 op_sel_hi:[1,0]
	v_rcp_f32_e32 v86, v86
	v_rcp_f32_e32 v87, v87
	v_rcp_f32_e32 v68, v68
	v_rcp_f32_e32 v69, v69
	v_pk_mul_f32 v[84:85], v[84:85], v[86:87]
	v_pk_mul_f32 v[2:3], v[2:3], v[68:69]
	s_and_saveexec_b64 s[16:17], s[4:5]
	s_xor_b64 s[94:95], exec, s[16:17]
	s_cbranch_execz .LBB0_378
	s_and_saveexec_b64 s[16:17], s[8:9]
	s_xor_b64 vcc, exec, s[16:17]
	s_cbranch_execz .LBB0_375
	v_cvt_pk_bf16_f32 v68, v72, v73
	v_add_u32_e32 v69, v205, v219
	ds_write_b32 v69, v68 offset:3584
	v_cvt_pk_bf16_f32 v68, v74, v75
	ds_write_b32 v212, v68 offset:6032
	v_cvt_pk_bf16_f32 v68, v76, v77
	ds_write_b32 v212, v68 offset:6304
	v_cvt_pk_bf16_f32 v68, v78, v79
	ds_write_b32 v212, v68 offset:6576
	v_cvt_pk_bf16_f32 v68, v80, v81
	ds_write_b32 v212, v68 offset:6848
	v_cvt_pk_bf16_f32 v68, v82, v83
	ds_write_b32 v212, v68 offset:7120
	v_cvt_pk_bf16_f32 v68, v84, v85
	ds_write_b32 v212, v68 offset:7392
	v_cvt_pk_bf16_f32 v2, v2, v3
	ds_write_b32 v212, v2 offset:7664

.LBB0_380:
	s_or_b64 exec, exec, s[94:95]
	s_add_i32 s14, s15, 1
	s_cmp_lt_u32 s14, s0
	s_cselect_b32 s15, s14, s15
	s_lshl_b32 s16, s15, 6
	v_add_u32_e32 v2, s13, v231
	s_add_i32 s16, s16, s97
	v_ashrrev_i32_e32 v3, 31, v2
	s_cmp_eq_u32 s15, 0
	v_lshlrev_b64 v[2:3], 12, v[2:3]
	s_cselect_b32 s15, 0, 0x1000
	v_lshl_add_u64 v[190:191], v[164:165], 0, v[2:3]
	v_add_u32_e32 v2, s16, v1
	v_mov_b32_e32 v84, s15
	v_ashrrev_i32_e32 v3, 31, v2
	v_cndmask_b32_e64 v86, v84, v195, s[6:7]
	v_lshlrev_b64 v[2:3], 13, v[2:3]
	v_mul_u32_u24_e32 v84, 3, v86
	v_lshl_add_u64 v[2:3], v[176:177], 0, v[2:3]
	v_lshlrev_b32_e32 v84, 1, v84
	v_sub_co_u32_e32 v84, vcc, v2, v84
	global_load_dwordx4 v[76:79], v[190:191], off
	global_load_dwordx4 v[80:83], v[190:191], off offset:128
	global_load_dwordx4 v[72:75], v[190:191], off offset:256
	global_load_dwordx4 v[68:71], v[190:191], off offset:384
	s_waitcnt lgkmcnt(0)
	s_barrier
	v_subbrev_co_u32_e32 v85, vcc, 0, v3, vcc
	global_load_dword v250, v[84:85], off
	v_lshlrev_b32_e32 v84, 2, v86
	v_sub_co_u32_e32 v84, vcc, v2, v84
	v_lshlrev_b32_e32 v87, 1, v86
	s_nop 0
	v_subbrev_co_u32_e32 v85, vcc, 0, v3, vcc
	global_load_dword v251, v[84:85], off
	v_sub_co_u32_e32 v84, vcc, v2, v87
	s_movk_i32 s15, 0x2000
	s_nop 0
	v_subbrev_co_u32_e32 v85, vcc, 0, v3, vcc
	global_load_dword v252, v[84:85], off
	global_load_dword v249, v[2:3], off
	v_add_co_u32_e32 v84, vcc, s15, v2
	s_movk_i32 s15, 0x4000
	s_nop 0
	v_addc_co_u32_e32 v85, vcc, 0, v3, vcc
	global_load_dword v248, v[84:85], off
	v_add_co_u32_e32 v84, vcc, s15, v2
	s_movk_i32 s15, 0x6000
	s_nop 0
	v_addc_co_u32_e32 v85, vcc, 0, v3, vcc
	global_load_dword v247, v[84:85], off
	v_add_co_u32_e32 v84, vcc, s15, v2
	s_mov_b32 s15, 0x8000
	s_nop 0
	v_addc_co_u32_e32 v85, vcc, 0, v3, vcc
	global_load_dword v246, v[84:85], off
	v_add_co_u32_e32 v84, vcc, s15, v2
	s_mov_b32 s15, 0xa000
	s_nop 0
	v_addc_co_u32_e32 v85, vcc, 0, v3, vcc
	global_load_dword v245, v[84:85], off
	v_add_co_u32_e32 v84, vcc, s15, v2
	s_mov_b32 s15, 0xc000
	s_nop 0
	v_addc_co_u32_e32 v85, vcc, 0, v3, vcc
	global_load_dword v244, v[84:85], off
	v_add_co_u32_e32 v84, vcc, s15, v2
	s_mov_b32 s15, 0xe000
	s_nop 0
	v_addc_co_u32_e32 v85, vcc, 0, v3, vcc
	global_load_dword v243, v[84:85], off
	v_add_co_u32_e32 v84, vcc, s15, v2
	s_mov_b32 s15, 0x10000
	s_nop 0
	v_addc_co_u32_e32 v85, vcc, 0, v3, vcc
	global_load_dword v242, v[84:85], off
	v_add_co_u32_e32 v84, vcc, s15, v2
	s_mov_b32 s15, 0x12000
	s_nop 0
	v_addc_co_u32_e32 v85, vcc, 0, v3, vcc
	global_load_dword v241, v[84:85], off
	v_add_co_u32_e32 v84, vcc, s15, v2
	s_mov_b32 s15, 0x14000
	s_nop 0
	v_addc_co_u32_e32 v85, vcc, 0, v3, vcc
	global_load_dword v240, v[84:85], off
	v_add_co_u32_e32 v84, vcc, s15, v2
	s_mov_b32 s15, 0x16000
	s_nop 0
	v_addc_co_u32_e32 v85, vcc, 0, v3, vcc
	global_load_dword v239, v[84:85], off
	v_add_co_u32_e32 v84, vcc, s15, v2
	s_mov_b32 s15, 0x18000
	s_nop 0
	v_addc_co_u32_e32 v85, vcc, 0, v3, vcc
	global_load_dword v238, v[84:85], off
	v_add_co_u32_e32 v84, vcc, s15, v2
	s_mov_b32 s15, 0x1a000
	s_nop 0
	v_addc_co_u32_e32 v85, vcc, 0, v3, vcc
	v_add_co_u32_e32 v2, vcc, s15, v2
	global_load_dword v237, v[84:85], off
	s_nop 0
	v_addc_co_u32_e32 v3, vcc, 0, v3, vcc
	global_load_dword v236, v[2:3], off
	v_add_u32_e32 v2, s16, v159
	v_ashrrev_i32_e32 v3, 31, v2
	v_lshlrev_b64 v[2:3], 7, v[2:3]
	v_lshl_add_u64 v[2:3], s[90:91], 0, v[2:3]
	global_load_dword v153, v[2:3], off
	ds_read_b128 v[84:87], v180
	ds_read_b128 v[88:91], v181 offset:17408
	ds_read_b128 v[92:95], v181 offset:21760
	ds_read_b128 v[104:107], v180 offset:64
	ds_read_b128 v[96:99], v181 offset:17472
	ds_read_b128 v[100:103], v181 offset:21824
	ds_read_b128 v[108:111], v180 offset:128
	ds_read_b128 v[112:115], v181 offset:17536
	v_add_u32_e32 v192, v178, v228
	ds_read_b128 v[116:119], v181 offset:21888
	ds_read_b128 v[120:123], v180 offset:192
	s_waitcnt lgkmcnt(8)
	v_mfma_f32_16x16x32_bf16 v[88:91], v[84:87], v[88:91], 0
	ds_read_b128 v[124:127], v181 offset:17600
	s_waitcnt lgkmcnt(8)
	v_mfma_f32_16x16x32_bf16 v[84:87], v[84:87], v[92:95], 0
	ds_read_b128 v[128:131], v181 offset:21952
	s_waitcnt lgkmcnt(7)
	v_mfma_f32_16x16x32_bf16 v[88:91], v[104:107], v[96:99], v[88:91]
	s_waitcnt lgkmcnt(6)
	v_mfma_f32_16x16x32_bf16 v[84:87], v[104:107], v[100:103], v[84:87]
	s_waitcnt lgkmcnt(4)
	v_mfma_f32_16x16x32_bf16 v[88:91], v[108:111], v[112:115], v[88:91]
	s_waitcnt lgkmcnt(3)
	v_mfma_f32_16x16x32_bf16 v[84:87], v[108:111], v[116:119], v[84:87]
	s_waitcnt lgkmcnt(1)
	v_mfma_f32_16x16x32_bf16 v[88:91], v[120:123], v[124:127], v[88:91]
	s_waitcnt lgkmcnt(0)
	v_mfma_f32_16x16x32_bf16 v[84:87], v[120:123], v[128:131], v[84:87]
	s_nop 7
	ds_write2_b32 v202, v88, v84 offset1:16
	ds_write2_b32 v202, v89, v85 offset0:68 offset1:84
	ds_write2_b32 v202, v90, v86 offset0:136 offset1:152
	ds_write2_b32 v202, v91, v87 offset0:204 offset1:220
	ds_read2_b64 v[92:95], v224 offset1:4
	ds_read2_b64 v[100:103], v225 offset1:4
	ds_read2_b64 v[108:111], v226 offset1:4
	ds_read2_b64 v[116:119], v227 offset1:4
	ds_read2_b64 v[124:127], v224 offset0:8 offset1:12
	ds_read2_b64 v[128:131], v225 offset0:8 offset1:12
	ds_read2_b64 v[132:135], v226 offset0:8 offset1:12
	ds_read2_b64 v[136:139], v227 offset0:8 offset1:12
	v_cvt_pk_bf16_f32 v84, v4, v5
	v_cvt_pk_bf16_f32 v85, v6, v7
	v_cvt_pk_bf16_f32 v86, v12, v13
	v_cvt_pk_bf16_f32 v87, v14, v15
	v_cvt_pk_bf16_f32 v88, v8, v9
	v_cvt_pk_bf16_f32 v89, v10, v11
	v_cvt_pk_bf16_f32 v90, v16, v17
	v_cvt_pk_bf16_f32 v91, v18, v19
	ds_read2_b64 v[140:143], v224 offset0:16 offset1:20
	s_waitcnt lgkmcnt(8)
	v_mfma_f32_16x16x32_bf16 v[96:99], v[92:95], v[84:87], 0
	v_mfma_f32_16x16x32_bf16 v[92:95], v[92:95], v[88:91], 0
	ds_read2_b64 v[144:147], v225 offset0:16 offset1:20
	s_waitcnt lgkmcnt(8)
	v_mfma_f32_16x16x32_bf16 v[104:107], v[100:103], v[84:87], 0
	v_mfma_f32_16x16x32_bf16 v[100:103], v[100:103], v[88:91], 0
	ds_read2_b64 v[148:151], v226 offset0:16 offset1:20
	s_waitcnt lgkmcnt(8)
	v_mfma_f32_16x16x32_bf16 v[112:115], v[108:111], v[84:87], 0
	v_mfma_f32_16x16x32_bf16 v[108:111], v[108:111], v[88:91], 0
	s_waitcnt lgkmcnt(7)
	v_mfma_f32_16x16x32_bf16 v[84:87], v[116:119], v[84:87], 0
	v_mfma_f32_16x16x32_bf16 v[88:91], v[116:119], v[88:91], 0
	v_cvt_pk_bf16_f32 v116, v20, v21
	v_cvt_pk_bf16_f32 v117, v22, v23
	v_cvt_pk_bf16_f32 v118, v28, v29
	v_cvt_pk_bf16_f32 v119, v30, v31
	v_cvt_pk_bf16_f32 v120, v24, v25
	v_cvt_pk_bf16_f32 v121, v26, v27
	v_cvt_pk_bf16_f32 v122, v32, v33
	v_cvt_pk_bf16_f32 v123, v34, v35
	s_waitcnt lgkmcnt(6)
	v_mfma_f32_16x16x32_bf16 v[96:99], v[124:127], v[116:119], v[96:99]
	v_mfma_f32_16x16x32_bf16 v[92:95], v[124:127], v[120:123], v[92:95]
	ds_read2_b64 v[124:127], v227 offset0:16 offset1:20
	s_waitcnt lgkmcnt(6)
	v_mfma_f32_16x16x32_bf16 v[104:107], v[128:131], v[116:119], v[104:107]
	v_mfma_f32_16x16x32_bf16 v[100:103], v[128:131], v[120:123], v[100:103]
	s_waitcnt lgkmcnt(5)
	v_mfma_f32_16x16x32_bf16 v[112:115], v[132:135], v[116:119], v[112:115]
	v_mfma_f32_16x16x32_bf16 v[108:111], v[132:135], v[120:123], v[108:111]
	s_waitcnt lgkmcnt(4)
	v_mfma_f32_16x16x32_bf16 v[84:87], v[136:139], v[116:119], v[84:87]
	v_cvt_pk_bf16_f32 v116, v36, v37
	v_cvt_pk_bf16_f32 v117, v38, v39
	v_cvt_pk_bf16_f32 v118, v44, v45
	v_mfma_f32_16x16x32_bf16 v[88:91], v[136:139], v[120:123], v[88:91]
	v_cvt_pk_bf16_f32 v119, v46, v47
	v_cvt_pk_bf16_f32 v120, v40, v41
	v_cvt_pk_bf16_f32 v121, v42, v43
	v_cvt_pk_bf16_f32 v122, v48, v49
	v_cvt_pk_bf16_f32 v123, v50, v51
	s_waitcnt lgkmcnt(3)
	v_mfma_f32_16x16x32_bf16 v[96:99], v[140:143], v[116:119], v[96:99]
	v_mfma_f32_16x16x32_bf16 v[92:95], v[140:143], v[120:123], v[92:95]
	s_waitcnt lgkmcnt(2)
	v_mfma_f32_16x16x32_bf16 v[104:107], v[144:147], v[116:119], v[104:107]
	v_mfma_f32_16x16x32_bf16 v[100:103], v[144:147], v[120:123], v[100:103]
	s_waitcnt lgkmcnt(1)
	v_mfma_f32_16x16x32_bf16 v[112:115], v[148:151], v[116:119], v[112:115]
	v_mfma_f32_16x16x32_bf16 v[108:111], v[148:151], v[120:123], v[108:111]
	s_waitcnt lgkmcnt(0)
	v_mfma_f32_16x16x32_bf16 v[84:87], v[124:127], v[116:119], v[84:87]
	v_mfma_f32_16x16x32_bf16 v[116:119], v[124:127], v[120:123], v[88:91]
	ds_read2_b64 v[124:127], v224 offset0:24 offset1:28
	s_nop 1
	v_cvt_pk_bf16_f32 v88, v52, v53
	v_cvt_pk_bf16_f32 v89, v54, v55
	v_cvt_pk_bf16_f32 v90, v60, v61
	v_cvt_pk_bf16_f32 v91, v62, v63
	v_cvt_pk_bf16_f32 v120, v56, v57
	v_cvt_pk_bf16_f32 v121, v58, v59
	v_cvt_pk_bf16_f32 v122, v64, v65
	v_cvt_pk_bf16_f32 v123, v66, v67
	s_waitcnt lgkmcnt(0)
	v_mfma_f32_16x16x32_bf16 v[128:131], v[124:127], v[88:91], v[96:99]
	v_mfma_f32_16x16x32_bf16 v[124:127], v[124:127], v[120:123], v[92:95]
	s_nop 2
	ds_read2_b64 v[92:95], v225 offset0:24 offset1:28
	s_nop 2
	s_waitcnt lgkmcnt(0)
	v_mfma_f32_16x16x32_bf16 v[104:107], v[92:95], v[88:91], v[104:107]
	v_mfma_f32_16x16x32_bf16 v[132:135], v[92:95], v[120:123], v[100:103]
	ds_read2_b64 v[92:95], v226 offset0:24 offset1:28
	s_waitcnt lgkmcnt(0)
	v_mfma_f32_16x16x32_bf16 v[100:103], v[92:95], v[88:91], v[112:115]
	v_mfma_f32_16x16x32_bf16 v[96:99], v[92:95], v[120:123], v[108:111]
	ds_read2_b64 v[92:95], v227 offset0:24 offset1:28
	s_waitcnt lgkmcnt(0)
	v_mfma_f32_16x16x32_bf16 v[88:91], v[92:95], v[88:91], v[84:87]
	v_mfma_f32_16x16x32_bf16 v[92:95], v[92:95], v[120:123], v[116:119]
	v_add_u32_e32 v120, s33, v156
	s_nop 0
	ds_read_b128 v[84:87], v120
	ds_read_b128 v[136:139], v120 offset:64
	ds_read_b128 v[140:143], v120 offset:128
	s_nop 0
	s_waitcnt lgkmcnt(2)
	v_mul_f32_e32 v2, 0x3fb8aa3b, v84
	v_mul_f32_e32 v84, 0x3fb8aa3b, v86
	v_exp_f32_e32 v108, v84
	v_mul_f32_e32 v84, 0x3fb8aa3b, v87
	v_exp_f32_e32 v109, v84
	v_mul_f32_e32 v3, 0x3fb8aa3b, v85
	v_exp_f32_e32 v2, v2
	v_exp_f32_e32 v3, v3
	v_pk_mul_f32 v[86:87], v[130:131], v[108:109]
	v_pk_mul_f32 v[118:119], v[126:127], v[108:109]
	v_pk_mul_f32 v[84:85], v[128:129], v[2:3]
	v_pk_mul_f32 v[116:117], v[124:125], v[2:3]
	s_waitcnt lgkmcnt(1)
	v_mul_f32_e32 v2, 0x3fb8aa3b, v136
	v_mul_f32_e32 v108, 0x3fb8aa3b, v138
	v_mul_f32_e32 v3, 0x3fb8aa3b, v137
	v_exp_f32_e32 v112, v108
	v_mul_f32_e32 v108, 0x3fb8aa3b, v139
	v_exp_f32_e32 v2, v2
	v_exp_f32_e32 v3, v3
	v_exp_f32_e32 v113, v108
	v_pk_mul_f32 v[108:109], v[104:105], v[2:3]
	v_pk_mul_f32 v[110:111], v[106:107], v[112:113]
	v_pk_mul_f32 v[114:115], v[134:135], v[112:113]
	v_pk_mul_f32 v[112:113], v[132:133], v[2:3]
	s_waitcnt lgkmcnt(0)
	v_mul_f32_e32 v2, 0x3fb8aa3b, v140
	v_mul_f32_e32 v3, 0x3fb8aa3b, v141
	v_mul_f32_e32 v104, 0x3fb8aa3b, v142
	v_mul_f32_e32 v105, 0x3fb8aa3b, v143
	v_exp_f32_e32 v2, v2
	v_exp_f32_e32 v3, v3
	v_exp_f32_e32 v104, v104
	v_exp_f32_e32 v105, v105
	v_pk_mul_f32 v[100:101], v[100:101], v[2:3]
	v_pk_mul_f32 v[102:103], v[102:103], v[104:105]
	v_pk_mul_f32 v[106:107], v[98:99], v[104:105]
	v_pk_mul_f32 v[104:105], v[96:97], v[2:3]
	ds_read_b128 v[96:99], v120 offset:192
	s_waitcnt vmcnt(21)
	ds_write_b128 v230, v[76:79]
	s_waitcnt vmcnt(20)
	ds_write_b128 v230, v[80:83] offset:128
	s_waitcnt vmcnt(19)
	ds_write_b128 v230, v[72:75] offset:256
	s_waitcnt vmcnt(18)
	ds_write_b128 v230, v[68:71] offset:384
	s_waitcnt lgkmcnt(0)
	s_barrier
	v_mul_f32_e32 v2, 0x3fb8aa3b, v96
	v_mul_f32_e32 v3, 0x3fb8aa3b, v97
	v_mul_f32_e32 v96, 0x3fb8aa3b, v98
	v_mul_f32_e32 v97, 0x3fb8aa3b, v99
	v_exp_f32_e32 v2, v2
	v_exp_f32_e32 v3, v3
	v_exp_f32_e32 v96, v96
	v_exp_f32_e32 v97, v97
	v_pk_mul_f32 v[88:89], v[88:89], v[2:3]
	v_pk_mul_f32 v[90:91], v[90:91], v[96:97]
	v_pk_mul_f32 v[98:99], v[94:95], v[96:97]
	v_pk_mul_f32 v[96:97], v[92:93], v[2:3]
	v_mov_b32_e32 v2, s33
	ds_read_b32 v253, v2 offset:252
	ds_read_b128 v[148:151], v209
	ds_read_b128 v[140:143], v209 offset:16
	ds_read_b128 v[144:147], v201
	ds_read_b128 v[124:127], v201 offset:16
	ds_read_b128 v[120:123], v192 offset:53248
	s_waitcnt lgkmcnt(5)
	v_mul_f32_e32 v2, 0x3fb8aa3b, v253
	v_exp_f32_e32 v2, v2
	s_nop 0
	v_pk_mul_f32 v[6:7], v[6:7], v[2:3] op_sel_hi:[1,0]
	v_pk_mul_f32 v[4:5], v[4:5], v[2:3] op_sel_hi:[1,0]
	v_pk_mul_f32 v[74:75], v[10:11], v[2:3] op_sel_hi:[1,0]
	v_pk_mul_f32 v[72:73], v[8:9], v[2:3] op_sel_hi:[1,0]
	v_pk_mul_f32 v[10:11], v[14:15], v[2:3] op_sel_hi:[1,0]
	v_pk_mul_f32 v[8:9], v[12:13], v[2:3] op_sel_hi:[1,0]
	v_pk_mul_f32 v[18:19], v[18:19], v[2:3] op_sel_hi:[1,0]
	v_pk_mul_f32 v[16:17], v[16:17], v[2:3] op_sel_hi:[1,0]
	v_pk_mul_f32 v[14:15], v[22:23], v[2:3] op_sel_hi:[1,0]
	v_pk_mul_f32 v[12:13], v[20:21], v[2:3] op_sel_hi:[1,0]
	v_pk_mul_f32 v[26:27], v[26:27], v[2:3] op_sel_hi:[1,0]
	v_pk_mul_f32 v[24:25], v[24:25], v[2:3] op_sel_hi:[1,0]
	v_pk_mul_f32 v[22:23], v[30:31], v[2:3] op_sel_hi:[1,0]
	v_pk_mul_f32 v[20:21], v[28:29], v[2:3] op_sel_hi:[1,0]
	v_pk_mul_f32 v[34:35], v[34:35], v[2:3] op_sel_hi:[1,0]
	v_pk_mul_f32 v[32:33], v[32:33], v[2:3] op_sel_hi:[1,0]
	v_pk_mul_f32 v[30:31], v[38:39], v[2:3] op_sel_hi:[1,0]
	v_pk_mul_f32 v[28:29], v[36:37], v[2:3] op_sel_hi:[1,0]
	v_pk_mul_f32 v[42:43], v[42:43], v[2:3] op_sel_hi:[1,0]
	v_pk_mul_f32 v[40:41], v[40:41], v[2:3] op_sel_hi:[1,0]
	v_pk_mul_f32 v[38:39], v[46:47], v[2:3] op_sel_hi:[1,0]
	v_pk_mul_f32 v[36:37], v[44:45], v[2:3] op_sel_hi:[1,0]
	v_pk_mul_f32 v[50:51], v[50:51], v[2:3] op_sel_hi:[1,0]
	v_pk_mul_f32 v[48:49], v[48:49], v[2:3] op_sel_hi:[1,0]
	v_pk_mul_f32 v[46:47], v[54:55], v[2:3] op_sel_hi:[1,0]
	v_pk_mul_f32 v[44:45], v[52:53], v[2:3] op_sel_hi:[1,0]
	v_pk_mul_f32 v[58:59], v[58:59], v[2:3] op_sel_hi:[1,0]
	v_pk_mul_f32 v[56:57], v[56:57], v[2:3] op_sel_hi:[1,0]
	v_pk_mul_f32 v[54:55], v[62:63], v[2:3] op_sel_hi:[1,0]
	v_pk_mul_f32 v[52:53], v[60:61], v[2:3] op_sel_hi:[1,0]
	v_pk_mul_f32 v[62:63], v[66:67], v[2:3] op_sel_hi:[1,0]
	v_pk_mul_f32 v[60:61], v[64:65], v[2:3] op_sel_hi:[1,0]
	ds_read_b128 v[64:67], v192 offset:55552
	ds_read_b32 v2, v229
	ds_read_b128 v[68:71], v232
	ds_read_b128 v[76:79], v232 offset:16
	s_waitcnt lgkmcnt(2)
	v_sub_f32_e32 v3, v2, v148
	v_mul_f32_e32 v3, 0x3fb8aa3b, v3
	v_exp_f32_e32 v3, v3
	s_waitcnt lgkmcnt(1)
	v_mul_f32_e32 v3, v68, v3
	v_sub_f32_e32 v68, v2, v149
	v_mul_f32_e32 v68, 0x3fb8aa3b, v68
	v_exp_f32_e32 v68, v68
	v_mul_f32_e32 v3, v144, v3
	v_cndmask_b32_e64 v3, v3, 0, s[24:25]
	v_mul_f32_e32 v68, v69, v68
	v_sub_f32_e32 v69, v2, v150
	v_mul_f32_e32 v69, 0x3fb8aa3b, v69
	v_exp_f32_e32 v69, v69
	v_mul_f32_e32 v68, v145, v68
	v_cndmask_b32_e64 v68, 0, v68, s[26:27]
	ds_read_b32 v80, v229 offset:64
	ds_read_b128 v[128:131], v232 offset:4352
	ds_read_b128 v[132:135], v232 offset:4368
	v_cvt_pk_bf16_f32 v68, v3, v68
	v_mul_f32_e32 v69, v70, v69
	v_sub_f32_e32 v70, v2, v151
	v_mul_f32_e32 v70, 0x3fb8aa3b, v70
	v_exp_f32_e32 v70, v70
	v_mul_f32_e32 v69, v146, v69
	v_cndmask_b32_e64 v69, v69, 0, s[28:29]
	v_mul_f32_e32 v70, v71, v70
	v_sub_f32_e32 v71, v2, v140
	v_mul_f32_e32 v71, 0x3fb8aa3b, v71
	v_exp_f32_e32 v71, v71
	v_mul_f32_e32 v70, v147, v70
	v_cndmask_b32_e64 v70, v70, 0, s[30:31]
	v_cvt_pk_bf16_f32 v69, v69, v70
	s_waitcnt lgkmcnt(3)
	v_mul_f32_e32 v71, v76, v71
	v_sub_f32_e32 v76, v2, v141
	v_mul_f32_e32 v76, 0x3fb8aa3b, v76
	v_exp_f32_e32 v76, v76
	v_mul_f32_e32 v71, v124, v71
	v_cndmask_b32_e64 v71, v71, 0, s[34:35]
	v_mul_f32_e32 v76, v77, v76
	v_sub_f32_e32 v77, v2, v142
	v_sub_f32_e32 v2, v2, v143
	v_mul_f32_e32 v77, 0x3fb8aa3b, v77
	v_mul_f32_e32 v2, 0x3fb8aa3b, v2
	v_exp_f32_e32 v77, v77
	v_exp_f32_e32 v2, v2
	v_mul_f32_e32 v76, v125, v76
	v_cndmask_b32_e64 v76, v76, 0, s[36:37]
	v_mul_f32_e32 v77, v78, v77
	v_mul_f32_e32 v2, v79, v2
	v_mul_f32_e32 v77, v126, v77
	v_mul_f32_e32 v2, v127, v2
	v_cndmask_b32_e64 v77, v77, 0, s[38:39]
	v_cndmask_b32_e64 v2, v2, 0, s[40:41]
	v_cvt_pk_bf16_f32 v70, v71, v76
	v_cvt_pk_bf16_f32 v71, v77, v2
	s_nop 0
	s_nop 0
	v_mfma_f32_16x16x32_bf16 v[92:95], v[68:71], v[120:123], v[84:87]
	v_mfma_f32_16x16x32_bf16 v[84:87], v[68:71], v[64:67], v[116:119]
	s_waitcnt lgkmcnt(2)
	v_sub_f32_e32 v3, v80, v148
	v_mul_f32_e32 v3, 0x3fb8aa3b, v3
	v_exp_f32_e32 v3, v3
	s_waitcnt lgkmcnt(1)
	v_mul_f32_e32 v3, v128, v3
	v_sub_f32_e32 v68, v80, v149
	v_mul_f32_e32 v68, 0x3fb8aa3b, v68
	v_exp_f32_e32 v68, v68
	v_mul_f32_e32 v3, v144, v3
	v_cndmask_b32_e64 v3, v3, 0, s[42:43]
	v_mul_f32_e32 v68, v129, v68
	v_sub_f32_e32 v69, v80, v150
	v_mul_f32_e32 v69, 0x3fb8aa3b, v69
	v_exp_f32_e32 v69, v69
	v_mul_f32_e32 v68, v145, v68
	ds_read_b32 v116, v229 offset:128
	ds_read_b128 v[136:139], v232 offset:8704
	v_cndmask_b32_e64 v68, 0, v68, s[44:45]
	v_cvt_pk_bf16_f32 v68, v3, v68
	v_mul_f32_e32 v69, v130, v69
	v_sub_f32_e32 v70, v80, v151
	v_mul_f32_e32 v70, 0x3fb8aa3b, v70
	v_exp_f32_e32 v70, v70
	v_mul_f32_e32 v69, v146, v69
	v_cndmask_b32_e64 v69, v69, 0, s[46:47]
	v_mul_f32_e32 v70, v131, v70
	v_sub_f32_e32 v71, v80, v140
	v_mul_f32_e32 v71, 0x3fb8aa3b, v71
	v_exp_f32_e32 v71, v71
	v_mul_f32_e32 v70, v147, v70
	v_cndmask_b32_e64 v70, v70, 0, s[48:49]
	v_cvt_pk_bf16_f32 v69, v69, v70
	s_waitcnt lgkmcnt(2)
	v_mul_f32_e32 v71, v132, v71
	v_sub_f32_e32 v76, v80, v141
	v_mul_f32_e32 v76, 0x3fb8aa3b, v76
	v_exp_f32_e32 v76, v76
	v_mul_f32_e32 v71, v124, v71
	v_cndmask_b32_e64 v71, v71, 0, s[50:51]
	v_mul_f32_e32 v76, v133, v76
	v_sub_f32_e32 v77, v80, v142
	v_sub_f32_e32 v2, v80, v143
	v_mul_f32_e32 v77, 0x3fb8aa3b, v77
	v_mul_f32_e32 v2, 0x3fb8aa3b, v2
	v_exp_f32_e32 v77, v77
	v_exp_f32_e32 v2, v2
	v_mul_f32_e32 v76, v125, v76
	v_cndmask_b32_e64 v76, v76, 0, s[52:53]
	v_mul_f32_e32 v77, v134, v77
	v_mul_f32_e32 v2, v135, v2
	v_mul_f32_e32 v77, v126, v77
	v_mul_f32_e32 v2, v127, v2
	v_cndmask_b32_e64 v77, v77, 0, s[54:55]
	v_cndmask_b32_e64 v2, v2, 0, s[56:57]
	v_cvt_pk_bf16_f32 v70, v71, v76
	v_cvt_pk_bf16_f32 v71, v77, v2
	s_nop 0
	s_nop 0
	v_mfma_f32_16x16x32_bf16 v[76:79], v[68:71], v[120:123], v[108:111]
	s_nop 2
	ds_read_b128 v[108:111], v232 offset:8720
	s_nop 0
	s_waitcnt lgkmcnt(2)
	v_sub_f32_e32 v3, v116, v148
	v_mul_f32_e32 v3, 0x3fb8aa3b, v3
	v_exp_f32_e32 v3, v3
	v_mfma_f32_16x16x32_bf16 v[68:71], v[68:71], v[64:67], v[112:115]
	s_waitcnt lgkmcnt(1)
	v_mul_f32_e32 v3, v136, v3
	v_sub_f32_e32 v80, v116, v149
	v_mul_f32_e32 v80, 0x3fb8aa3b, v80
	v_exp_f32_e32 v80, v80
	ds_read_b32 v112, v229 offset:192
	ds_read_b128 v[128:131], v232 offset:13056
	v_mul_f32_e32 v3, v144, v3
	v_mul_f32_e32 v80, v137, v80
	v_sub_f32_e32 v81, v116, v150
	v_mul_f32_e32 v81, 0x3fb8aa3b, v81
	v_exp_f32_e32 v81, v81
	v_mul_f32_e32 v80, v145, v80
	v_cvt_pk_bf16_f32 v80, v3, v80
	v_mul_f32_e32 v81, v138, v81
	v_sub_f32_e32 v82, v116, v151
	v_mul_f32_e32 v82, 0x3fb8aa3b, v82
	v_exp_f32_e32 v82, v82
	v_mul_f32_e32 v81, v146, v81
	v_mul_f32_e32 v82, v139, v82
	v_sub_f32_e32 v83, v116, v140
	v_mul_f32_e32 v83, 0x3fb8aa3b, v83
	v_exp_f32_e32 v83, v83
	v_mul_f32_e32 v82, v147, v82
	v_cvt_pk_bf16_f32 v81, v81, v82
	s_waitcnt lgkmcnt(2)
	v_mul_f32_e32 v83, v108, v83
	v_sub_f32_e32 v108, v116, v141
	v_mul_f32_e32 v108, 0x3fb8aa3b, v108
	v_exp_f32_e32 v108, v108
	v_mul_f32_e32 v83, v124, v83
	v_mul_f32_e32 v108, v109, v108
	v_sub_f32_e32 v109, v116, v142
	v_sub_f32_e32 v2, v116, v143
	v_mul_f32_e32 v109, 0x3fb8aa3b, v109
	v_mul_f32_e32 v2, 0x3fb8aa3b, v2
	v_exp_f32_e32 v109, v109
	v_exp_f32_e32 v2, v2
	v_mul_f32_e32 v108, v125, v108
	v_cvt_pk_bf16_f32 v82, v83, v108
	v_mul_f32_e32 v109, v110, v109
	v_mul_f32_e32 v2, v111, v2
	v_mul_f32_e32 v109, v126, v109
	v_mul_f32_e32 v2, v127, v2
	v_cvt_pk_bf16_f32 v83, v109, v2
	s_nop 0
	s_nop 0
	v_mfma_f32_16x16x32_bf16 v[132:135], v[80:83], v[120:123], v[100:103]
	s_nop 2
	ds_read_b128 v[100:103], v232 offset:13072
	v_mfma_f32_16x16x32_bf16 v[136:139], v[80:83], v[64:67], v[104:107]
	s_waitcnt lgkmcnt(2)
	v_sub_f32_e32 v3, v112, v148
	v_mul_f32_e32 v3, 0x3fb8aa3b, v3
	v_exp_f32_e32 v3, v3
	s_waitcnt lgkmcnt(1)
	v_mul_f32_e32 v3, v128, v3
	v_sub_f32_e32 v80, v112, v149
	v_mul_f32_e32 v80, 0x3fb8aa3b, v80
	v_exp_f32_e32 v80, v80
	v_mul_f32_e32 v3, v144, v3
	v_mul_f32_e32 v80, v129, v80
	v_sub_f32_e32 v81, v112, v150
	v_mul_f32_e32 v81, 0x3fb8aa3b, v81
	v_exp_f32_e32 v81, v81
	v_mul_f32_e32 v80, v145, v80
	v_mul_f32_e32 v81, v130, v81
	v_sub_f32_e32 v82, v112, v151
	v_mul_f32_e32 v82, 0x3fb8aa3b, v82
	v_exp_f32_e32 v82, v82
	v_mul_f32_e32 v81, v146, v81
	v_mul_f32_e32 v82, v131, v82
	v_sub_f32_e32 v83, v112, v140
	v_mul_f32_e32 v83, 0x3fb8aa3b, v83
	v_exp_f32_e32 v83, v83
	v_mul_f32_e32 v82, v147, v82
	s_waitcnt lgkmcnt(0)
	v_mul_f32_e32 v83, v100, v83
	v_sub_f32_e32 v100, v112, v141
	v_mul_f32_e32 v100, 0x3fb8aa3b, v100
	v_exp_f32_e32 v100, v100
	v_mul_f32_e32 v83, v124, v83
	v_mul_f32_e32 v100, v101, v100
	v_mul_f32_e32 v104, v125, v100
	v_sub_f32_e32 v100, v112, v142
	v_sub_f32_e32 v2, v112, v143
	v_mul_f32_e32 v100, 0x3fb8aa3b, v100
	v_mul_f32_e32 v2, 0x3fb8aa3b, v2
	v_exp_f32_e32 v100, v100
	v_exp_f32_e32 v2, v2
	v_mul_f32_e32 v100, v102, v100
	v_mul_f32_e32 v2, v103, v2
	v_mul_f32_e32 v105, v126, v100
	v_mul_f32_e32 v2, v127, v2
	v_cvt_pk_bf16_f32 v100, v3, v80
	v_cvt_pk_bf16_f32 v101, v81, v82
	v_cvt_pk_bf16_f32 v102, v83, v104
	v_cvt_pk_bf16_f32 v103, v105, v2
	v_sub_f32_e32 v2, v253, v148
	s_nop 0
	v_mfma_f32_16x16x32_bf16 v[80:83], v[100:103], v[120:123], v[88:91]
	v_sub_f32_e32 v3, v253, v149
	v_mul_f32_e32 v2, 0x3fb8aa3b, v2
	v_mul_f32_e32 v3, 0x3fb8aa3b, v3
	v_sub_f32_e32 v88, v253, v150
	v_mul_f32_e32 v88, 0x3fb8aa3b, v88
	v_exp_f32_e32 v88, v88
	v_mfma_f32_16x16x32_bf16 v[128:131], v[100:103], v[64:67], v[96:99]
	v_exp_f32_e32 v2, v2
	v_exp_f32_e32 v3, v3
	v_and_b32_e32 v89, 0xffff0000, v120
	v_mul_f32_e32 v96, v146, v88
	v_sub_f32_e32 v88, v253, v151
	v_mul_f32_e32 v88, 0x3fb8aa3b, v88
	v_exp_f32_e32 v88, v88
	v_mul_f32_e32 v2, v144, v2
	v_mul_f32_e32 v3, v145, v3
	v_lshlrev_b32_e32 v90, 16, v121
	v_mul_f32_e32 v97, v147, v88
	v_sub_f32_e32 v88, v253, v140
	v_mul_f32_e32 v88, 0x3fb8aa3b, v88
	v_exp_f32_e32 v88, v88
	v_lshlrev_b32_e32 v102, 16, v122
	v_mul_f32_e32 v89, v3, v89
	v_mul_f32_e32 v90, v96, v90
	v_mul_f32_e32 v98, v124, v88
	v_sub_f32_e32 v88, v253, v141
	v_mul_f32_e32 v88, 0x3fb8aa3b, v88
	v_exp_f32_e32 v88, v88
	v_and_b32_e32 v91, 0xffff0000, v121
	v_mul_f32_e32 v102, v98, v102
	v_and_b32_e32 v103, 0xffff0000, v122
	v_mul_f32_e32 v99, v125, v88
	ds_read_b128 v[106:109], v233 offset:34816
	v_sub_f32_e32 v88, v253, v142
	v_mul_f32_e32 v88, 0x3fb8aa3b, v88
	ds_read_b128 v[110:113], v233 offset:37120
	v_exp_f32_e32 v88, v88
	v_mul_f32_e32 v91, v97, v91
	ds_read_b128 v[114:117], v233 offset:39424
	v_mul_f32_e32 v103, v99, v103
	v_lshlrev_b32_e32 v104, 16, v123
	ds_read_b128 v[144:147], v233 offset:41728
	v_mul_f32_e32 v100, v126, v88
	v_sub_f32_e32 v88, v253, v143
	ds_read_b128 v[148:151], v233 offset:44032
	v_mul_f32_e32 v88, 0x3fb8aa3b, v88
	v_exp_f32_e32 v88, v88
	v_and_b32_e32 v105, 0xffff0000, v123
	v_mul_f32_e32 v104, v100, v104
	v_mul_f32_e32 v101, v127, v88
	v_lshlrev_b32_e32 v88, 16, v120
	v_mul_f32_e32 v88, v2, v88
	v_cvt_pk_bf16_f32 v88, v88, v89
	v_cvt_pk_bf16_f32 v89, v90, v91
	v_cvt_pk_bf16_f32 v90, v102, v103
	v_lshlrev_b32_e32 v102, 16, v64
	v_and_b32_e32 v64, 0xffff0000, v64
	v_mul_f32_e32 v3, v3, v64
	v_lshlrev_b32_e32 v64, 16, v65
	v_mul_f32_e32 v64, v96, v64
	v_lshlrev_b32_e32 v96, 16, v66
	v_and_b32_e32 v65, 0xffff0000, v65
	v_mul_f32_e32 v98, v98, v96
	v_and_b32_e32 v66, 0xffff0000, v66
	v_lshlrev_b32_e32 v96, 16, v67
	v_and_b32_e32 v67, 0xffff0000, v67
	v_mul_f32_e32 v65, v97, v65
	v_mul_f32_e32 v66, v99, v66
	v_mul_f32_e32 v99, v100, v96
	v_mul_f32_e32 v67, v101, v67
	v_mul_f32_e32 v105, v101, v105
	v_cvt_pk_bf16_f32 v91, v104, v105
	v_mul_f32_e32 v2, v2, v102
	v_cvt_pk_bf16_f32 v96, v2, v3
	v_cvt_pk_bf16_f32 v97, v64, v65
	v_cvt_pk_bf16_f32 v98, v98, v66
	v_cvt_pk_bf16_f32 v99, v99, v67
	s_waitcnt lgkmcnt(4)
	v_mfma_f32_16x16x32_bf16 v[2:5], v[106:109], v[88:91], v[4:7]
	v_mfma_f32_16x16x32_bf16 v[140:143], v[106:109], v[96:99], v[72:75]
	s_waitcnt lgkmcnt(3)
	v_mfma_f32_16x16x32_bf16 v[120:123], v[110:113], v[88:91], v[8:11]
	s_nop 2
	ds_read_b128 v[6:9], v233 offset:46336
	s_nop 2
	s_waitcnt lgkmcnt(3)
	v_mfma_f32_16x16x32_bf16 v[124:127], v[114:117], v[88:91], v[12:15]
	v_mfma_f32_16x16x32_bf16 v[24:27], v[114:117], v[96:99], v[24:27]
	s_waitcnt lgkmcnt(2)
	v_mfma_f32_16x16x32_bf16 v[116:119], v[144:147], v[88:91], v[20:23]
	v_mfma_f32_16x16x32_bf16 v[32:35], v[144:147], v[96:99], v[32:35]
	v_mfma_f32_16x16x32_bf16 v[16:19], v[110:113], v[96:99], v[16:19]
	s_waitcnt lgkmcnt(1)
	v_mfma_f32_16x16x32_bf16 v[64:67], v[148:151], v[88:91], v[28:31]
	v_mfma_f32_16x16x32_bf16 v[40:43], v[148:151], v[96:99], v[40:43]
	s_waitcnt lgkmcnt(0)
	v_mfma_f32_16x16x32_bf16 v[100:103], v[6:9], v[88:91], v[36:39]
	v_mfma_f32_16x16x32_bf16 v[48:51], v[6:9], v[96:99], v[48:51]
	ds_read_b128 v[6:9], v233 offset:48640
	s_waitcnt lgkmcnt(0)
	v_mfma_f32_16x16x32_bf16 v[104:107], v[6:9], v[88:91], v[44:47]
	v_mfma_f32_16x16x32_bf16 v[56:59], v[6:9], v[96:99], v[56:59]
	ds_read_b128 v[6:9], v233 offset:50944
	s_nop 0
	ds_read_b128 v[44:47], v209 offset:128
	ds_read_b128 v[28:31], v209 offset:144
	ds_read_b128 v[36:39], v201 offset:128
	ds_read_b128 v[20:23], v201 offset:144
	ds_read_b128 v[10:13], v192 offset:53312
	s_waitcnt lgkmcnt(5)
	v_mfma_f32_16x16x32_bf16 v[108:111], v[6:9], v[88:91], v[52:55]
	v_mfma_f32_16x16x32_bf16 v[112:115], v[6:9], v[96:99], v[60:63]
	ds_read_b128 v[6:9], v192 offset:55616
	ds_read_b32 v14, v229 offset:128
	ds_read_b128 v[52:55], v232 offset:8832
	ds_read_b128 v[60:63], v232 offset:8848
	s_waitcnt lgkmcnt(2)
	v_sub_f32_e32 v15, v14, v44
	v_mul_f32_e32 v15, 0x3fb8aa3b, v15
	v_exp_f32_e32 v15, v15
	s_waitcnt lgkmcnt(1)
	v_mul_f32_e32 v15, v52, v15
	v_sub_f32_e32 v52, v14, v45
	v_mul_f32_e32 v52, 0x3fb8aa3b, v52
	v_exp_f32_e32 v52, v52
	v_mul_f32_e32 v15, v36, v15
	v_cndmask_b32_e64 v15, v15, 0, s[24:25]
	v_mul_f32_e32 v52, v53, v52
	v_sub_f32_e32 v53, v14, v46
	v_mul_f32_e32 v53, 0x3fb8aa3b, v53
	v_exp_f32_e32 v53, v53
	v_mul_f32_e32 v52, v37, v52
	v_cndmask_b32_e64 v52, v52, 0, s[58:59]
	ds_read_b32 v72, v229 offset:192
	ds_read_b128 v[144:147], v232 offset:13184
	ds_read_b128 v[148:151], v232 offset:13200
	v_cvt_pk_bf16_f32 v52, v15, v52
	v_mul_f32_e32 v53, v54, v53
	v_sub_f32_e32 v54, v14, v47
	v_mul_f32_e32 v54, 0x3fb8aa3b, v54
	v_exp_f32_e32 v54, v54
	v_mul_f32_e32 v53, v38, v53
	v_cndmask_b32_e64 v53, v53, 0, s[60:61]
	v_mul_f32_e32 v54, v55, v54
	v_sub_f32_e32 v55, v14, v28
	v_mul_f32_e32 v55, 0x3fb8aa3b, v55
	v_exp_f32_e32 v55, v55
	v_mul_f32_e32 v54, v39, v54
	v_cndmask_b32_e64 v54, v54, 0, s[62:63]
	v_cvt_pk_bf16_f32 v53, v53, v54
	s_waitcnt lgkmcnt(3)
	v_mul_f32_e32 v55, v60, v55
	v_sub_f32_e32 v60, v14, v29
	v_mul_f32_e32 v60, 0x3fb8aa3b, v60
	v_exp_f32_e32 v60, v60
	v_mul_f32_e32 v55, v20, v55
	v_cndmask_b32_e64 v55, v55, 0, s[64:65]
	v_mul_f32_e32 v60, v61, v60
	v_sub_f32_e32 v61, v14, v30
	v_sub_f32_e32 v14, v14, v31
	v_mul_f32_e32 v61, 0x3fb8aa3b, v61
	v_mul_f32_e32 v14, 0x3fb8aa3b, v14
	v_exp_f32_e32 v61, v61
	v_exp_f32_e32 v14, v14
	v_mul_f32_e32 v60, v21, v60
	v_cndmask_b32_e64 v60, v60, 0, s[66:67]
	v_mul_f32_e32 v61, v62, v61
	v_mul_f32_e32 v14, v63, v14
	v_mul_f32_e32 v61, v22, v61
	v_mul_f32_e32 v14, v23, v14
	v_cndmask_b32_e64 v61, v61, 0, s[68:69]
	v_cndmask_b32_e64 v14, v14, 0, s[70:71]
	v_cvt_pk_bf16_f32 v54, v55, v60
	v_cvt_pk_bf16_f32 v55, v61, v14
	s_nop 0
	s_nop 0
	v_mfma_f32_16x16x32_bf16 v[96:99], v[52:55], v[10:13], v[132:135]
	v_mfma_f32_16x16x32_bf16 v[88:91], v[52:55], v[6:9], v[136:139]
	s_waitcnt lgkmcnt(2)
	v_sub_f32_e32 v15, v72, v44
	v_mul_f32_e32 v15, 0x3fb8aa3b, v15
	v_exp_f32_e32 v15, v15
	s_waitcnt lgkmcnt(1)
	v_mul_f32_e32 v15, v144, v15
	v_sub_f32_e32 v52, v72, v45
	v_mul_f32_e32 v52, 0x3fb8aa3b, v52
	v_exp_f32_e32 v52, v52
	v_mul_f32_e32 v15, v36, v15
	v_cndmask_b32_e64 v15, v15, 0, s[72:73]
	v_mul_f32_e32 v52, v145, v52
	v_sub_f32_e32 v53, v72, v46
	v_mul_f32_e32 v53, 0x3fb8aa3b, v53
	v_exp_f32_e32 v53, v53
	v_mul_f32_e32 v52, v37, v52
	v_cndmask_b32_e64 v52, v52, 0, s[74:75]
	v_cvt_pk_bf16_f32 v52, v15, v52
	v_mul_f32_e32 v53, v146, v53
	v_sub_f32_e32 v54, v72, v47
	v_mul_f32_e32 v54, 0x3fb8aa3b, v54
	v_exp_f32_e32 v54, v54
	v_mul_f32_e32 v53, v38, v53
	v_cndmask_b32_e64 v53, v53, 0, s[76:77]
	v_sub_f32_e32 v15, v253, v45
	v_mul_f32_e32 v54, v147, v54
	v_sub_f32_e32 v55, v72, v28
	v_mul_f32_e32 v55, 0x3fb8aa3b, v55
	v_exp_f32_e32 v55, v55
	v_sub_f32_e32 v28, v253, v28
	v_mul_f32_e32 v28, 0x3fb8aa3b, v28
	v_exp_f32_e32 v28, v28
	s_waitcnt lgkmcnt(0)
	v_mul_f32_e32 v55, v148, v55
	v_sub_f32_e32 v60, v72, v29
	v_mul_f32_e32 v60, 0x3fb8aa3b, v60
	v_exp_f32_e32 v60, v60
	v_mul_f32_e32 v55, v20, v55
	v_mul_f32_e32 v20, v20, v28
	v_sub_f32_e32 v28, v253, v29
	v_mul_f32_e32 v60, v149, v60
	v_sub_f32_e32 v61, v72, v30
	v_sub_f32_e32 v14, v72, v31
	v_mul_f32_e32 v14, 0x3fb8aa3b, v14
	v_mul_f32_e32 v61, 0x3fb8aa3b, v61
	v_exp_f32_e32 v14, v14
	v_exp_f32_e32 v61, v61
	v_mul_f32_e32 v28, 0x3fb8aa3b, v28
	v_exp_f32_e32 v28, v28
	v_mul_f32_e32 v14, v151, v14
	v_mul_f32_e32 v54, v39, v54
	v_mul_f32_e32 v61, v150, v61
	v_mul_f32_e32 v14, v23, v14
	v_cndmask_b32_e64 v54, v54, 0, s[78:79]
	v_cndmask_b32_e64 v55, v55, 0, s[80:81]
	v_mul_f32_e32 v60, v21, v60
	v_mul_f32_e32 v61, v22, v61
	v_cndmask_b32_e64 v14, v14, 0, s[86:87]
	v_mul_f32_e32 v21, v21, v28
	v_sub_f32_e32 v28, v253, v30
	v_cndmask_b32_e64 v60, v60, 0, s[82:83]
	v_cndmask_b32_e64 v61, v61, 0, s[84:85]
	v_cvt_pk_bf16_f32 v53, v53, v54
	v_cvt_pk_bf16_f32 v54, v55, v60
	v_cvt_pk_bf16_f32 v55, v61, v14
	v_sub_f32_e32 v14, v253, v44
	v_mul_f32_e32 v15, 0x3fb8aa3b, v15
	v_mul_f32_e32 v28, 0x3fb8aa3b, v28
	v_mul_f32_e32 v14, 0x3fb8aa3b, v14
	v_exp_f32_e32 v15, v15
	v_exp_f32_e32 v28, v28
	v_exp_f32_e32 v14, v14
	v_mfma_f32_16x16x32_bf16 v[80:83], v[52:55], v[10:13], v[80:83]
	v_mul_f32_e32 v15, v37, v15
	v_sub_f32_e32 v37, v253, v47
	v_mul_f32_e32 v22, v22, v28
	v_sub_f32_e32 v28, v253, v31
	v_mul_f32_e32 v14, v36, v14
	v_sub_f32_e32 v36, v253, v46
	v_mul_f32_e32 v37, 0x3fb8aa3b, v37
	v_mul_f32_e32 v28, 0x3fb8aa3b, v28
	v_mul_f32_e32 v36, 0x3fb8aa3b, v36
	v_exp_f32_e32 v37, v37
	v_exp_f32_e32 v28, v28
	v_exp_f32_e32 v36, v36
	v_lshlrev_b32_e32 v29, 16, v11
	v_mul_f32_e32 v37, v39, v37
	v_mul_f32_e32 v23, v23, v28
	v_lshlrev_b32_e32 v28, 16, v10
	ds_read_b128 v[132:135], v233 offset:34880
	ds_read_b128 v[136:139], v233 offset:37184
	ds_read_b128 v[144:147], v233 offset:39488
	ds_read_b128 v[148:151], v233 offset:41792
	ds_read_b128 v[44:47], v233 offset:44096
	v_and_b32_e32 v10, 0xffff0000, v10
	v_and_b32_e32 v11, 0xffff0000, v11
	v_lshlrev_b32_e32 v30, 16, v12
	v_and_b32_e32 v12, 0xffff0000, v12
	v_lshlrev_b32_e32 v31, 16, v13
	v_and_b32_e32 v13, 0xffff0000, v13
	v_mul_f32_e32 v36, v38, v36
	v_mul_f32_e32 v10, v15, v10
	v_mul_f32_e32 v11, v37, v11
	v_mul_f32_e32 v12, v21, v12
	v_mul_f32_e32 v13, v23, v13
	v_mfma_f32_16x16x32_bf16 v[72:75], v[52:55], v[6:9], v[128:131]
	ds_read_b128 v[52:55], v233 offset:46400
	v_mul_f32_e32 v28, v14, v28
	v_mul_f32_e32 v29, v36, v29
	v_mul_f32_e32 v30, v20, v30
	v_mul_f32_e32 v31, v22, v31
	v_cvt_pk_bf16_f32 v60, v28, v10
	v_cvt_pk_bf16_f32 v61, v29, v11
	v_cvt_pk_bf16_f32 v62, v30, v12
	v_cvt_pk_bf16_f32 v63, v31, v13
	v_lshlrev_b32_e32 v10, 16, v6
	v_lshlrev_b32_e32 v11, 16, v7
	v_lshlrev_b32_e32 v12, 16, v8
	v_and_b32_e32 v8, 0xffff0000, v8
	v_lshlrev_b32_e32 v13, 16, v9
	v_and_b32_e32 v9, 0xffff0000, v9
	v_mul_f32_e32 v10, v14, v10
	v_and_b32_e32 v6, 0xffff0000, v6
	v_mul_f32_e32 v11, v36, v11
	v_and_b32_e32 v7, 0xffff0000, v7
	v_mul_f32_e32 v8, v21, v8
	v_mul_f32_e32 v9, v23, v9
	v_mul_f32_e32 v6, v15, v6
	v_mul_f32_e32 v7, v37, v7
	v_mul_f32_e32 v12, v20, v12
	v_mul_f32_e32 v13, v22, v13
	v_cvt_pk_bf16_f32 v128, v10, v6
	v_cvt_pk_bf16_f32 v129, v11, v7
	v_cvt_pk_bf16_f32 v130, v12, v8
	v_cvt_pk_bf16_f32 v131, v13, v9
	s_waitcnt lgkmcnt(4)
	v_mfma_f32_16x16x32_bf16 v[12:15], v[136:139], v[60:63], v[120:123]
	v_mfma_f32_16x16x32_bf16 v[16:19], v[136:139], v[128:131], v[16:19]
	s_waitcnt lgkmcnt(3)
	v_mfma_f32_16x16x32_bf16 v[20:23], v[144:147], v[60:63], v[124:127]
	v_mfma_f32_16x16x32_bf16 v[24:27], v[144:147], v[128:131], v[24:27]
	s_waitcnt lgkmcnt(2)
	v_mfma_f32_16x16x32_bf16 v[28:31], v[148:151], v[60:63], v[116:119]
	v_mfma_f32_16x16x32_bf16 v[32:35], v[148:151], v[128:131], v[32:35]
	s_waitcnt lgkmcnt(1)
	v_mfma_f32_16x16x32_bf16 v[36:39], v[44:47], v[60:63], v[64:67]
	s_nop 2
	ds_read_b128 v[64:67], v233 offset:48704
	s_nop 2
	v_mfma_f32_16x16x32_bf16 v[4:7], v[132:135], v[60:63], v[2:5]
	s_nop 2
	ds_read_b64 v[2:3], v234 offset:53248
	ds_read_u16 v192, v235
	v_mfma_f32_16x16x32_bf16 v[40:43], v[44:47], v[128:131], v[40:43]
	s_nop 1
	s_waitcnt lgkmcnt(3)
	v_mfma_f32_16x16x32_bf16 v[44:47], v[52:55], v[60:63], v[100:103]
	s_nop 2
	ds_read_u16 v103, v235 offset:528
	v_mfma_f32_16x16x32_bf16 v[48:51], v[52:55], v[128:131], v[48:51]
	s_nop 1
	s_waitcnt lgkmcnt(2)
	v_lshlrev_b32_e32 v100, 16, v2
	v_mfma_f32_16x16x32_bf16 v[52:55], v[64:67], v[60:63], v[104:107]
	v_and_b32_e32 v101, 0xffff0000, v2
	s_waitcnt lgkmcnt(1)
	v_lshlrev_b32_e32 v102, 16, v192
	s_waitcnt lgkmcnt(0)
	v_lshlrev_b32_e32 v103, 16, v103
	v_mfma_f32_16x16x32_bf16 v[56:59], v[64:67], v[128:131], v[56:59]
	ds_read_b128 v[64:67], v233 offset:51008
	ds_read_u16 v116, v235 offset:1056
	ds_read_u16 v117, v235 offset:1584
	ds_read_b64 v[104:105], v234 offset:55552
	ds_read_u16 v106, v235 offset:32
	ds_read_u16 v107, v235 offset:560
	v_pk_fma_f32 v[92:93], v[154:155], v[100:101], v[92:93]
	v_pk_mul_f32 v[100:101], v[102:103], s[96:97] op_sel_hi:[1,0]
	v_lshlrev_b32_e32 v2, 16, v3
	v_exp_f32_e32 v100, v100
	v_exp_f32_e32 v101, v101
	v_and_b32_e32 v3, 0xffff0000, v3
	v_pk_fma_f32 v[2:3], v[154:155], v[2:3], v[94:95]
	v_mfma_f32_16x16x32_bf16 v[8:11], v[132:135], v[128:131], v[140:143]
	v_add_f32_e64 v100, v100, 1.0
	v_add_f32_e64 v101, v101, 1.0
	v_rcp_f32_e32 v100, v100
	v_rcp_f32_e32 v101, v101
	s_waitcnt lgkmcnt(5)
	v_mfma_f32_16x16x32_bf16 v[60:63], v[64:67], v[60:63], v[108:111]
	v_mul_f32_e64 v100, v100, v102
	v_mul_f32_e64 v101, v101, v103
	v_pk_mul_f32 v[92:93], v[92:93], v[100:101]
	v_mfma_f32_16x16x32_bf16 v[64:67], v[64:67], v[128:131], v[112:115]
	v_cvt_pk_bf16_f32 v102, v92, v93
	ds_write_b16 v235, v102
	ds_write_b16_d16_hi v235, v102 offset:528
	s_waitcnt lgkmcnt(6)
	v_lshlrev_b32_e32 v92, 16, v116
	s_waitcnt lgkmcnt(5)
	v_lshlrev_b32_e32 v93, 16, v117
	ds_read_u16 v100, v235 offset:1088
	ds_read_u16 v101, v235 offset:1616
	v_pk_mul_f32 v[94:95], v[92:93], s[96:97] op_sel_hi:[1,0]
	s_nop 0
	v_exp_f32_e32 v94, v94
	v_exp_f32_e32 v95, v95
	s_nop 0
	v_pk_add_f32 v[94:95], v[94:95], 1.0 op_sel_hi:[1,0]
	s_nop 0
	v_rcp_f32_e32 v94, v94
	v_rcp_f32_e32 v95, v95
	s_nop 0
	v_pk_mul_f32 v[92:93], v[94:95], v[92:93]
	s_nop 0
	v_pk_mul_f32 v[2:3], v[2:3], v[92:93]
	s_nop 0
	v_cvt_pk_bf16_f32 v103, v2, v3
	ds_write_b16 v235, v103 offset:1056
	ds_write_b16_d16_hi v235, v103 offset:1584
	s_waitcnt lgkmcnt(8)
	v_lshlrev_b32_e32 v92, 16, v104
	v_and_b32_e32 v93, 0xffff0000, v104
	s_waitcnt lgkmcnt(7)
	v_lshlrev_b32_e32 v94, 16, v106
	s_waitcnt lgkmcnt(6)
	v_lshlrev_b32_e32 v95, 16, v107
	v_pk_fma_f32 v[84:85], v[154:155], v[92:93], v[84:85]
	v_pk_mul_f32 v[92:93], v[94:95], s[96:97] op_sel_hi:[1,0]
	v_lshlrev_b32_e32 v2, 16, v105
	v_exp_f32_e32 v92, v92
	v_exp_f32_e32 v93, v93
	v_and_b32_e32 v3, 0xffff0000, v105
	v_pk_fma_f32 v[2:3], v[154:155], v[2:3], v[86:87]
	v_pk_add_f32 v[92:93], v[92:93], 1.0 op_sel_hi:[1,0]
	s_nop 0
	v_rcp_f32_e32 v92, v92
	v_rcp_f32_e32 v93, v93
	s_nop 0
	v_pk_mul_f32 v[92:93], v[92:93], v[94:95]
	s_nop 0
	v_pk_mul_f32 v[84:85], v[84:85], v[92:93]
	s_nop 0
	v_cvt_pk_bf16_f32 v92, v84, v85
	ds_write_b16 v235, v92 offset:32
	ds_write_b16_d16_hi v235, v92 offset:560
	s_waitcnt lgkmcnt(5)
	v_lshlrev_b32_e32 v84, 16, v100
	s_waitcnt lgkmcnt(4)
	v_lshlrev_b32_e32 v85, 16, v101
	v_pk_mul_f32 v[86:87], v[84:85], s[96:97] op_sel_hi:[1,0]
	s_nop 0
	v_exp_f32_e32 v86, v86
	v_exp_f32_e32 v87, v87
	s_nop 0
	v_pk_add_f32 v[86:87], v[86:87], 1.0 op_sel_hi:[1,0]
	s_nop 0
	v_rcp_f32_e32 v86, v86
	v_rcp_f32_e32 v87, v87
	s_nop 0
	v_pk_mul_f32 v[84:85], v[86:87], v[84:85]
	s_nop 0
	v_pk_mul_f32 v[2:3], v[2:3], v[84:85]
	v_lshlrev_b32_e32 v84, 16, v92
	v_cvt_pk_bf16_f32 v93, v2, v3
	v_and_b32_e32 v3, 64, v199
	v_xor_b32_e32 v2, 1, v199
	v_add_u32_e32 v3, 64, v3
	v_cmp_lt_i32_e32 vcc, v2, v3
	ds_write_b16 v235, v93 offset:1088
	ds_write_b16_d16_hi v235, v93 offset:1616
	v_cndmask_b32_e32 v2, v199, v2, vcc
	v_lshlrev_b32_e32 v101, 2, v2
	v_xor_b32_e32 v2, 2, v199
	v_cmp_lt_i32_e32 vcc, v2, v3
	v_and_b32_e32 v85, 0xffff0000, v92
	v_lshlrev_b32_e32 v92, 16, v93
	v_cndmask_b32_e32 v2, v199, v2, vcc
	v_lshlrev_b32_e32 v100, 2, v2
	v_xor_b32_e32 v2, 4, v199
	v_cmp_lt_i32_e32 vcc, v2, v3
	v_and_b32_e32 v93, 0xffff0000, v93
	v_pk_mul_f32 v[84:85], v[84:85], v[84:85]
	v_cndmask_b32_e32 v2, v199, v2, vcc
	v_lshlrev_b32_e32 v95, 2, v2
	v_xor_b32_e32 v2, 8, v199
	v_cmp_lt_i32_e32 vcc, v2, v3
	v_and_b32_e32 v3, 0xffff0000, v102
	v_lshlrev_b32_e32 v86, 16, v103
	v_cndmask_b32_e32 v2, v199, v2, vcc
	v_lshlrev_b32_e32 v94, 2, v2
	v_lshlrev_b32_e32 v2, 16, v102
	v_and_b32_e32 v87, 0xffff0000, v103
	v_pk_mul_f32 v[92:93], v[92:93], v[92:93]
	v_pk_fma_f32 v[2:3], v[2:3], v[2:3], v[84:85]
	v_pk_fma_f32 v[86:87], v[86:87], v[86:87], v[92:93]
	s_nop 0
	v_add_u32_e32 v102, s12, v156
	v_add_f32_dpp v2, v2, v2 quad_perm:[1,0,3,2] row_mask:0xf bank_mask:0xf
	v_add_f32_dpp v3, v3, v3 quad_perm:[1,0,3,2] row_mask:0xf bank_mask:0xf
	v_add_f32_dpp v86, v86, v86 quad_perm:[1,0,3,2] row_mask:0xf bank_mask:0xf
	v_add_f32_dpp v87, v87, v87 quad_perm:[1,0,3,2] row_mask:0xf bank_mask:0xf
	v_add_f32_dpp v2, v2, v2 quad_perm:[2,3,0,1] row_mask:0xf bank_mask:0xf
	v_add_f32_dpp v3, v3, v3 quad_perm:[2,3,0,1] row_mask:0xf bank_mask:0xf
	v_add_f32_dpp v86, v86, v86 quad_perm:[2,3,0,1] row_mask:0xf bank_mask:0xf
	v_add_f32_dpp v87, v87, v87 quad_perm:[2,3,0,1] row_mask:0xf bank_mask:0xf
	v_add_f32_dpp v2, v2, v2 row_half_mirror row_mask:0xf bank_mask:0xf
	v_add_f32_dpp v3, v3, v3 row_half_mirror row_mask:0xf bank_mask:0xf
	v_add_f32_dpp v86, v86, v86 row_half_mirror row_mask:0xf bank_mask:0xf
	v_add_f32_dpp v87, v87, v87 row_half_mirror row_mask:0xf bank_mask:0xf
	v_add_f32_dpp v84, v2, v2 row_mirror row_mask:0xf bank_mask:0xf
	v_add_f32_dpp v85, v3, v3 row_mirror row_mask:0xf bank_mask:0xf
	v_add_f32_dpp v86, v86, v86 row_mirror row_mask:0xf bank_mask:0xf
	v_add_f32_dpp v87, v87, v87 row_mirror row_mask:0xf bank_mask:0xf
	s_and_saveexec_b64 s[94:95], s[10:11]
	s_cbranch_execz .LBB0_382
	ds_write_b128 v102, v[84:87]
.LBB0_382:
	s_or_b64 exec, exec, s[94:95]
	ds_read_b64 v[2:3], v234 offset:53280
	ds_read_u16 v86, v235 offset:8448
	ds_read_u16 v87, v235 offset:8976
	ds_read_u16 v92, v235 offset:9504
	ds_read_u16 v93, v235 offset:10032
	s_waitcnt lgkmcnt(4)
	v_lshlrev_b32_e32 v84, 16, v2
	v_and_b32_e32 v85, 0xffff0000, v2
	ds_read_b64 v[104:105], v234 offset:55584
	ds_read_u16 v103, v235 offset:8480
	ds_read_u16 v106, v235 offset:9008
	s_waitcnt lgkmcnt(6)
	v_lshlrev_b32_e32 v86, 16, v86
	s_waitcnt lgkmcnt(5)
	v_lshlrev_b32_e32 v87, 16, v87
	v_pk_fma_f32 v[76:77], v[154:155], v[84:85], v[76:77]
	v_pk_mul_f32 v[84:85], v[86:87], s[96:97] op_sel_hi:[1,0]
	v_lshlrev_b32_e32 v2, 16, v3
	v_exp_f32_e32 v84, v84
	v_exp_f32_e32 v85, v85
	v_and_b32_e32 v3, 0xffff0000, v3
	v_pk_fma_f32 v[2:3], v[154:155], v[2:3], v[78:79]
	v_pk_add_f32 v[84:85], v[84:85], 1.0 op_sel_hi:[1,0]
	s_nop 0
	v_rcp_f32_e32 v84, v84
	v_rcp_f32_e32 v85, v85
	s_nop 0
	v_pk_mul_f32 v[84:85], v[84:85], v[86:87]
	s_nop 0
	v_pk_mul_f32 v[76:77], v[76:77], v[84:85]
	s_nop 0
	v_cvt_pk_bf16_f32 v84, v76, v77
	ds_write_b16 v235, v84 offset:8448
	ds_write_b16_d16_hi v235, v84 offset:8976
	s_waitcnt lgkmcnt(6)
	v_lshlrev_b32_e32 v76, 16, v92
	s_waitcnt lgkmcnt(5)
	v_lshlrev_b32_e32 v77, 16, v93
	ds_read_u16 v86, v235 offset:9536
	ds_read_u16 v87, v235 offset:10064
	v_pk_mul_f32 v[78:79], v[76:77], s[96:97] op_sel_hi:[1,0]
	s_nop 0
	v_exp_f32_e32 v78, v78
	v_exp_f32_e32 v79, v79
	s_nop 0
	v_pk_add_f32 v[78:79], v[78:79], 1.0 op_sel_hi:[1,0]
	s_nop 0
	v_rcp_f32_e32 v78, v78
	v_rcp_f32_e32 v79, v79
	s_nop 0
	v_pk_mul_f32 v[76:77], v[78:79], v[76:77]
	s_nop 0
	v_pk_mul_f32 v[2:3], v[2:3], v[76:77]
	s_nop 0
	v_cvt_pk_bf16_f32 v85, v2, v3
	ds_write_b16 v235, v85 offset:9504
	ds_write_b16_d16_hi v235, v85 offset:10032
	s_waitcnt lgkmcnt(8)
	v_lshlrev_b32_e32 v76, 16, v104
	v_and_b32_e32 v77, 0xffff0000, v104
	s_waitcnt lgkmcnt(7)
	v_lshlrev_b32_e32 v78, 16, v103
	s_waitcnt lgkmcnt(6)
	v_lshlrev_b32_e32 v79, 16, v106
	v_pk_fma_f32 v[68:69], v[154:155], v[76:77], v[68:69]
	v_pk_mul_f32 v[76:77], v[78:79], s[96:97] op_sel_hi:[1,0]
	v_lshlrev_b32_e32 v2, 16, v105
	v_exp_f32_e32 v76, v76
	v_exp_f32_e32 v77, v77
	v_and_b32_e32 v3, 0xffff0000, v105
	v_pk_fma_f32 v[2:3], v[154:155], v[2:3], v[70:71]
	v_pk_add_f32 v[76:77], v[76:77], 1.0 op_sel_hi:[1,0]
	s_nop 0
	v_rcp_f32_e32 v76, v76
	v_rcp_f32_e32 v77, v77
	s_nop 0
	v_pk_mul_f32 v[76:77], v[76:77], v[78:79]
	s_nop 0
	v_pk_mul_f32 v[68:69], v[68:69], v[76:77]
	s_nop 0
	v_cvt_pk_bf16_f32 v76, v68, v69
	ds_write_b16 v235, v76 offset:8480
	ds_write_b16_d16_hi v235, v76 offset:9008
	s_waitcnt lgkmcnt(5)
	v_lshlrev_b32_e32 v68, 16, v86
	s_waitcnt lgkmcnt(4)
	v_lshlrev_b32_e32 v69, 16, v87
	v_pk_mul_f32 v[70:71], v[68:69], s[96:97] op_sel_hi:[1,0]
	s_nop 0
	v_exp_f32_e32 v70, v70
	v_exp_f32_e32 v71, v71
	s_nop 0
	v_pk_add_f32 v[70:71], v[70:71], 1.0 op_sel_hi:[1,0]
	s_nop 0
	v_rcp_f32_e32 v70, v70
	v_rcp_f32_e32 v71, v71
	s_nop 0
	v_pk_mul_f32 v[68:69], v[70:71], v[68:69]
	s_nop 0
	v_pk_mul_f32 v[2:3], v[2:3], v[68:69]
	v_lshlrev_b32_e32 v68, 16, v76
	v_cvt_pk_bf16_f32 v77, v2, v3
	ds_write_b16 v235, v77 offset:9536
	ds_write_b16_d16_hi v235, v77 offset:10064
	v_and_b32_e32 v69, 0xffff0000, v76
	v_lshlrev_b32_e32 v76, 16, v77
	v_and_b32_e32 v77, 0xffff0000, v77
	v_lshlrev_b32_e32 v2, 16, v84
	v_and_b32_e32 v3, 0xffff0000, v84
	v_pk_mul_f32 v[68:69], v[68:69], v[68:69]
	v_lshlrev_b32_e32 v70, 16, v85
	v_and_b32_e32 v71, 0xffff0000, v85
	v_pk_mul_f32 v[76:77], v[76:77], v[76:77]
	v_pk_fma_f32 v[2:3], v[2:3], v[2:3], v[68:69]
	v_pk_fma_f32 v[70:71], v[70:71], v[70:71], v[76:77]
	s_nop 0
	v_add_f32_dpp v2, v2, v2 quad_perm:[1,0,3,2] row_mask:0xf bank_mask:0xf
	v_add_f32_dpp v3, v3, v3 quad_perm:[1,0,3,2] row_mask:0xf bank_mask:0xf
	v_add_f32_dpp v70, v70, v70 quad_perm:[1,0,3,2] row_mask:0xf bank_mask:0xf
	v_add_f32_dpp v71, v71, v71 quad_perm:[1,0,3,2] row_mask:0xf bank_mask:0xf
	v_add_f32_dpp v2, v2, v2 quad_perm:[2,3,0,1] row_mask:0xf bank_mask:0xf
	v_add_f32_dpp v3, v3, v3 quad_perm:[2,3,0,1] row_mask:0xf bank_mask:0xf
	v_add_f32_dpp v70, v70, v70 quad_perm:[2,3,0,1] row_mask:0xf bank_mask:0xf
	v_add_f32_dpp v71, v71, v71 quad_perm:[2,3,0,1] row_mask:0xf bank_mask:0xf
	v_add_f32_dpp v2, v2, v2 row_half_mirror row_mask:0xf bank_mask:0xf
	v_add_f32_dpp v3, v3, v3 row_half_mirror row_mask:0xf bank_mask:0xf
	v_add_f32_dpp v70, v70, v70 row_half_mirror row_mask:0xf bank_mask:0xf
	v_add_f32_dpp v71, v71, v71 row_half_mirror row_mask:0xf bank_mask:0xf
	v_add_f32_dpp v68, v2, v2 row_mirror row_mask:0xf bank_mask:0xf
	v_add_f32_dpp v69, v3, v3 row_mirror row_mask:0xf bank_mask:0xf
	v_add_f32_dpp v70, v70, v70 row_mirror row_mask:0xf bank_mask:0xf
	v_add_f32_dpp v71, v71, v71 row_mirror row_mask:0xf bank_mask:0xf
	s_and_saveexec_b64 s[94:95], s[10:11]
	s_cbranch_execz .LBB0_384
	ds_write_b128 v102, v[68:71] offset:64
.LBB0_384:
	s_or_b64 exec, exec, s[94:95]
	ds_read_b64 v[2:3], v234 offset:53312
	ds_read_u16 v70, v235 offset:16896
	ds_read_u16 v71, v235 offset:17424
	ds_read_u16 v79, v235 offset:17952
	ds_read_u16 v86, v235 offset:18480
	s_waitcnt lgkmcnt(4)
	v_lshlrev_b32_e32 v68, 16, v2
	ds_read_b64 v[92:93], v234 offset:55616
	ds_read_u16 v87, v235 offset:16928
	ds_read_u16 v103, v235 offset:17456
	s_waitcnt lgkmcnt(6)
	v_lshlrev_b32_e32 v70, 16, v70
	s_waitcnt lgkmcnt(5)
	v_lshlrev_b32_e32 v71, 16, v71
	v_pk_mul_f32 v[76:77], v[70:71], s[96:97] op_sel_hi:[1,0]
	v_and_b32_e32 v69, 0xffff0000, v2
	v_exp_f32_e32 v76, v76
	v_exp_f32_e32 v77, v77
	v_pk_fma_f32 v[68:69], v[154:155], v[68:69], v[96:97]
	v_lshlrev_b32_e32 v2, 16, v3
	v_and_b32_e32 v3, 0xffff0000, v3
	v_pk_add_f32 v[76:77], v[76:77], 1.0 op_sel_hi:[1,0]
	v_pk_fma_f32 v[2:3], v[154:155], v[2:3], v[98:99]
	v_rcp_f32_e32 v76, v76
	v_rcp_f32_e32 v77, v77
	s_nop 0
	v_pk_mul_f32 v[70:71], v[76:77], v[70:71]
	s_nop 0
	v_pk_mul_f32 v[68:69], v[68:69], v[70:71]
	s_nop 0
	v_cvt_pk_bf16_f32 v78, v68, v69
	ds_write_b16 v235, v78 offset:16896
	ds_write_b16_d16_hi v235, v78 offset:17424
	s_waitcnt lgkmcnt(6)
	v_lshlrev_b32_e32 v68, 16, v79
	ds_read_u16 v96, v235 offset:17984
	ds_read_u16 v97, v235 offset:18512
	s_waitcnt lgkmcnt(7)
	v_lshlrev_b32_e32 v69, 16, v86
	v_pk_mul_f32 v[70:71], v[68:69], s[96:97] op_sel_hi:[1,0]
	s_nop 0
	v_exp_f32_e32 v70, v70
	v_exp_f32_e32 v71, v71
	s_nop 0
	v_pk_add_f32 v[70:71], v[70:71], 1.0 op_sel_hi:[1,0]
	s_nop 0
	v_rcp_f32_e32 v70, v70
	v_rcp_f32_e32 v71, v71
	s_nop 0
	v_pk_mul_f32 v[68:69], v[70:71], v[68:69]
	s_nop 0
	v_pk_mul_f32 v[2:3], v[2:3], v[68:69]
	s_nop 0
	v_cvt_pk_bf16_f32 v79, v2, v3
	ds_write_b16 v235, v79 offset:17952
	ds_write_b16_d16_hi v235, v79 offset:18480
	s_waitcnt lgkmcnt(8)
	v_lshlrev_b32_e32 v68, 16, v92
	s_waitcnt lgkmcnt(7)
	v_lshlrev_b32_e32 v70, 16, v87
	s_waitcnt lgkmcnt(6)
	v_lshlrev_b32_e32 v71, 16, v103
	v_pk_mul_f32 v[76:77], v[70:71], s[96:97] op_sel_hi:[1,0]
	v_and_b32_e32 v69, 0xffff0000, v92
	v_exp_f32_e32 v76, v76
	v_exp_f32_e32 v77, v77
	v_pk_fma_f32 v[68:69], v[154:155], v[68:69], v[88:89]
	v_lshlrev_b32_e32 v2, 16, v93
	v_and_b32_e32 v3, 0xffff0000, v93
	v_pk_add_f32 v[76:77], v[76:77], 1.0 op_sel_hi:[1,0]
	v_pk_fma_f32 v[2:3], v[154:155], v[2:3], v[90:91]
	v_rcp_f32_e32 v76, v76
	v_rcp_f32_e32 v77, v77
	s_nop 0
	v_pk_mul_f32 v[70:71], v[76:77], v[70:71]
	s_nop 0
	v_pk_mul_f32 v[68:69], v[68:69], v[70:71]
	s_nop 0
	v_cvt_pk_bf16_f32 v76, v68, v69
	ds_write_b16 v235, v76 offset:16928
	ds_write_b16_d16_hi v235, v76 offset:17456
	s_waitcnt lgkmcnt(5)
	v_lshlrev_b32_e32 v68, 16, v96
	s_waitcnt lgkmcnt(4)
	v_lshlrev_b32_e32 v69, 16, v97
	v_pk_mul_f32 v[70:71], v[68:69], s[96:97] op_sel_hi:[1,0]
	s_nop 0
	v_exp_f32_e32 v70, v70
	v_exp_f32_e32 v71, v71
	s_nop 0
	v_pk_add_f32 v[70:71], v[70:71], 1.0 op_sel_hi:[1,0]
	s_nop 0
	v_rcp_f32_e32 v70, v70
	v_rcp_f32_e32 v71, v71
	s_nop 0
	v_pk_mul_f32 v[68:69], v[70:71], v[68:69]
	s_nop 0
	v_pk_mul_f32 v[2:3], v[2:3], v[68:69]
	v_lshlrev_b32_e32 v68, 16, v76
	v_cvt_pk_bf16_f32 v77, v2, v3
	ds_write_b16 v235, v77 offset:17984
	ds_write_b16_d16_hi v235, v77 offset:18512
	v_and_b32_e32 v69, 0xffff0000, v76
	v_lshlrev_b32_e32 v76, 16, v77
	v_and_b32_e32 v77, 0xffff0000, v77
	v_lshlrev_b32_e32 v2, 16, v78
	v_and_b32_e32 v3, 0xffff0000, v78
	v_pk_mul_f32 v[68:69], v[68:69], v[68:69]
	v_lshlrev_b32_e32 v70, 16, v79
	v_and_b32_e32 v71, 0xffff0000, v79
	v_pk_mul_f32 v[76:77], v[76:77], v[76:77]
	v_pk_fma_f32 v[2:3], v[2:3], v[2:3], v[68:69]
	v_pk_fma_f32 v[70:71], v[70:71], v[70:71], v[76:77]
	s_nop 0
	v_add_f32_dpp v2, v2, v2 quad_perm:[1,0,3,2] row_mask:0xf bank_mask:0xf
	v_add_f32_dpp v3, v3, v3 quad_perm:[1,0,3,2] row_mask:0xf bank_mask:0xf
	v_add_f32_dpp v70, v70, v70 quad_perm:[1,0,3,2] row_mask:0xf bank_mask:0xf
	v_add_f32_dpp v71, v71, v71 quad_perm:[1,0,3,2] row_mask:0xf bank_mask:0xf
	v_add_f32_dpp v2, v2, v2 quad_perm:[2,3,0,1] row_mask:0xf bank_mask:0xf
	v_add_f32_dpp v3, v3, v3 quad_perm:[2,3,0,1] row_mask:0xf bank_mask:0xf
	v_add_f32_dpp v70, v70, v70 quad_perm:[2,3,0,1] row_mask:0xf bank_mask:0xf
	v_add_f32_dpp v71, v71, v71 quad_perm:[2,3,0,1] row_mask:0xf bank_mask:0xf
	v_add_f32_dpp v2, v2, v2 row_half_mirror row_mask:0xf bank_mask:0xf
	v_add_f32_dpp v3, v3, v3 row_half_mirror row_mask:0xf bank_mask:0xf
	v_add_f32_dpp v70, v70, v70 row_half_mirror row_mask:0xf bank_mask:0xf
	v_add_f32_dpp v71, v71, v71 row_half_mirror row_mask:0xf bank_mask:0xf
	v_add_f32_dpp v68, v2, v2 row_mirror row_mask:0xf bank_mask:0xf
	v_add_f32_dpp v69, v3, v3 row_mirror row_mask:0xf bank_mask:0xf
	v_add_f32_dpp v70, v70, v70 row_mirror row_mask:0xf bank_mask:0xf
	v_add_f32_dpp v71, v71, v71 row_mirror row_mask:0xf bank_mask:0xf
	s_and_saveexec_b64 s[94:95], s[10:11]
	s_cbranch_execz .LBB0_386
	ds_write_b128 v102, v[68:71] offset:128
.LBB0_386:
	s_or_b64 exec, exec, s[94:95]
	ds_read_b64 v[2:3], v234 offset:53344
	ds_read_u16 v70, v235 offset:25344
	ds_read_u16 v71, v235 offset:25872
	ds_read_u16 v86, v235 offset:26400
	ds_read_u16 v87, v235 offset:26928
	s_waitcnt lgkmcnt(4)
	v_lshlrev_b32_e32 v68, 16, v2
	ds_read_b64 v[88:89], v234 offset:55648
	ds_read_u16 v90, v235 offset:25376
	ds_read_u16 v91, v235 offset:25904
	s_waitcnt lgkmcnt(6)
	v_lshlrev_b32_e32 v70, 16, v70
	s_waitcnt lgkmcnt(5)
	v_lshlrev_b32_e32 v71, 16, v71
	v_pk_mul_f32 v[76:77], v[70:71], s[96:97] op_sel_hi:[1,0]
	v_and_b32_e32 v69, 0xffff0000, v2
	v_exp_f32_e32 v76, v76
	v_exp_f32_e32 v77, v77
	v_pk_fma_f32 v[68:69], v[154:155], v[68:69], v[80:81]
	v_lshlrev_b32_e32 v2, 16, v3
	v_and_b32_e32 v3, 0xffff0000, v3
	v_pk_add_f32 v[76:77], v[76:77], 1.0 op_sel_hi:[1,0]
	v_pk_fma_f32 v[2:3], v[154:155], v[2:3], v[82:83]
	v_rcp_f32_e32 v76, v76
	v_rcp_f32_e32 v77, v77
	s_nop 0
	v_pk_mul_f32 v[70:71], v[76:77], v[70:71]
	s_nop 0
	v_pk_mul_f32 v[68:69], v[68:69], v[70:71]
	s_nop 0
	v_cvt_pk_bf16_f32 v76, v68, v69
	ds_write_b16 v235, v76 offset:25344
	ds_write_b16_d16_hi v235, v76 offset:25872
	s_waitcnt lgkmcnt(6)
	v_lshlrev_b32_e32 v68, 16, v86
	s_waitcnt lgkmcnt(5)
	v_lshlrev_b32_e32 v69, 16, v87
	ds_read_u16 v86, v235 offset:26432
	ds_read_u16 v87, v235 offset:26960
	v_pk_mul_f32 v[70:71], v[68:69], s[96:97] op_sel_hi:[1,0]
	s_nop 0
	v_exp_f32_e32 v70, v70
	v_exp_f32_e32 v71, v71
	s_nop 0
	v_pk_add_f32 v[70:71], v[70:71], 1.0 op_sel_hi:[1,0]
	s_nop 0
	v_rcp_f32_e32 v70, v70
	v_rcp_f32_e32 v71, v71
	s_nop 0
	v_pk_mul_f32 v[68:69], v[70:71], v[68:69]
	s_nop 0
	v_pk_mul_f32 v[2:3], v[2:3], v[68:69]
	s_nop 0
	v_cvt_pk_bf16_f32 v77, v2, v3
	ds_write_b16 v235, v77 offset:26400
	ds_write_b16_d16_hi v235, v77 offset:26928
	s_waitcnt lgkmcnt(8)
	v_lshlrev_b32_e32 v68, 16, v88
	v_and_b32_e32 v69, 0xffff0000, v88
	s_waitcnt lgkmcnt(7)
	v_lshlrev_b32_e32 v70, 16, v90
	s_waitcnt lgkmcnt(6)
	v_lshlrev_b32_e32 v71, 16, v91
	v_pk_fma_f32 v[68:69], v[154:155], v[68:69], v[72:73]
	v_pk_mul_f32 v[72:73], v[70:71], s[96:97] op_sel_hi:[1,0]
	v_lshlrev_b32_e32 v2, 16, v89
	v_exp_f32_e32 v72, v72
	v_exp_f32_e32 v73, v73
	v_and_b32_e32 v3, 0xffff0000, v89
	v_pk_fma_f32 v[2:3], v[154:155], v[2:3], v[74:75]
	v_pk_add_f32 v[72:73], v[72:73], 1.0 op_sel_hi:[1,0]
	s_nop 0
	v_rcp_f32_e32 v72, v72
	v_rcp_f32_e32 v73, v73
	s_nop 0
	v_pk_mul_f32 v[70:71], v[72:73], v[70:71]
	s_nop 0
	v_pk_mul_f32 v[68:69], v[68:69], v[70:71]
	s_nop 0
	v_cvt_pk_bf16_f32 v72, v68, v69
	ds_write_b16 v235, v72 offset:25376
	ds_write_b16_d16_hi v235, v72 offset:25904
	s_waitcnt lgkmcnt(5)
	v_lshlrev_b32_e32 v68, 16, v86
	s_waitcnt lgkmcnt(4)
	v_lshlrev_b32_e32 v69, 16, v87
	v_pk_mul_f32 v[70:71], v[68:69], s[96:97] op_sel_hi:[1,0]
	s_nop 0
	v_exp_f32_e32 v70, v70
	v_exp_f32_e32 v71, v71
	s_nop 0
	v_pk_add_f32 v[70:71], v[70:71], 1.0 op_sel_hi:[1,0]
	s_nop 0
	v_rcp_f32_e32 v70, v70
	v_rcp_f32_e32 v71, v71
	s_nop 0
	v_pk_mul_f32 v[68:69], v[70:71], v[68:69]
	s_nop 0
	v_pk_mul_f32 v[2:3], v[2:3], v[68:69]
	v_lshlrev_b32_e32 v68, 16, v72
	v_cvt_pk_bf16_f32 v73, v2, v3
	ds_write_b16 v235, v73 offset:26432
	ds_write_b16_d16_hi v235, v73 offset:26960
	v_and_b32_e32 v69, 0xffff0000, v72
	v_lshlrev_b32_e32 v72, 16, v73
	v_and_b32_e32 v73, 0xffff0000, v73
	v_lshlrev_b32_e32 v2, 16, v76
	v_and_b32_e32 v3, 0xffff0000, v76
	v_pk_mul_f32 v[68:69], v[68:69], v[68:69]
	v_lshlrev_b32_e32 v70, 16, v77
	v_and_b32_e32 v71, 0xffff0000, v77
	v_pk_mul_f32 v[72:73], v[72:73], v[72:73]
	v_pk_fma_f32 v[2:3], v[2:3], v[2:3], v[68:69]
	v_pk_fma_f32 v[70:71], v[70:71], v[70:71], v[72:73]
	s_nop 0
	v_add_f32_dpp v2, v2, v2 quad_perm:[1,0,3,2] row_mask:0xf bank_mask:0xf
	v_add_f32_dpp v3, v3, v3 quad_perm:[1,0,3,2] row_mask:0xf bank_mask:0xf
	v_add_f32_dpp v70, v70, v70 quad_perm:[1,0,3,2] row_mask:0xf bank_mask:0xf
	v_add_f32_dpp v71, v71, v71 quad_perm:[1,0,3,2] row_mask:0xf bank_mask:0xf
	v_add_f32_dpp v2, v2, v2 quad_perm:[2,3,0,1] row_mask:0xf bank_mask:0xf
	v_add_f32_dpp v3, v3, v3 quad_perm:[2,3,0,1] row_mask:0xf bank_mask:0xf
	v_add_f32_dpp v70, v70, v70 quad_perm:[2,3,0,1] row_mask:0xf bank_mask:0xf
	v_add_f32_dpp v71, v71, v71 quad_perm:[2,3,0,1] row_mask:0xf bank_mask:0xf
	v_add_f32_dpp v2, v2, v2 row_half_mirror row_mask:0xf bank_mask:0xf
	v_add_f32_dpp v3, v3, v3 row_half_mirror row_mask:0xf bank_mask:0xf
	v_add_f32_dpp v70, v70, v70 row_half_mirror row_mask:0xf bank_mask:0xf
	v_add_f32_dpp v71, v71, v71 row_half_mirror row_mask:0xf bank_mask:0xf
	v_add_f32_dpp v68, v2, v2 row_mirror row_mask:0xf bank_mask:0xf
	v_add_f32_dpp v69, v3, v3 row_mirror row_mask:0xf bank_mask:0xf
	v_add_f32_dpp v70, v70, v70 row_mirror row_mask:0xf bank_mask:0xf
	v_add_f32_dpp v71, v71, v71 row_mirror row_mask:0xf bank_mask:0xf
	s_and_saveexec_b64 s[94:95], s[10:11]
	s_cbranch_execz .LBB0_388
	ds_write_b128 v102, v[68:71] offset:192
.LBB0_388:
	s_or_b64 exec, exec, s[94:95]
	s_waitcnt lgkmcnt(0)
	s_barrier
	ds_read2st64_b32 v[2:3], v210 offset1:1
	ds_read2st64_b32 v[70:71], v210 offset0:2 offset1:3
	ds_read2st64_b32 v[72:73], v210 offset0:4 offset1:5
	ds_read2st64_b32 v[74:75], v210 offset0:6 offset1:7
	ds_read_b128 v[86:89], v230
	ds_read_b128 v[90:93], v230 offset:128
	s_mov_b32 s15, 0x800000
	s_add_i32 s13, s13, 64
	s_cmp_lg_u32 s14, s0
	s_waitcnt lgkmcnt(5)
	v_add_f32_e32 v2, 0, v2
	v_add_f32_e32 v68, v2, v3
	s_waitcnt lgkmcnt(4)
	v_add_f32_e32 v2, v68, v70
	v_add_f32_e32 v68, v2, v71
	s_waitcnt lgkmcnt(3)
	v_add_f32_e32 v2, v68, v72
	v_add_f32_e32 v68, v2, v73
	s_waitcnt lgkmcnt(2)
	v_add_f32_e32 v2, v68, v74
	v_add_f32_e32 v2, v2, v75
	v_fmamk_f32 v2, v2, 0x3b800000, v194
	ds_read_b128 v[94:97], v230 offset:256
	v_cmp_gt_f32_e32 vcc, s15, v2
	v_mul_f32_e32 v3, 0x4b800000, v2
	s_nop 0
	v_cndmask_b32_e32 v2, v2, v3, vcc
	v_rsq_f32_e32 v2, v2
	s_waitcnt lgkmcnt(2)
	v_lshlrev_b32_e32 v72, 16, v86
	v_mul_f32_e32 v3, 0x45800000, v2
	v_cndmask_b32_e32 v2, v2, v3, vcc
	v_and_b32_e32 v73, 0xffff0000, v86
	v_lshlrev_b32_e32 v68, 16, v87
	v_and_b32_e32 v69, 0xffff0000, v87
	v_lshlrev_b32_e32 v74, 16, v88
	v_and_b32_e32 v75, 0xffff0000, v88
	v_lshlrev_b32_e32 v70, 16, v89
	v_and_b32_e32 v71, 0xffff0000, v89
	v_pk_mul_f32 v[76:77], v[2:3], v[68:69] op_sel_hi:[0,1]
	v_pk_mul_f32 v[68:69], v[2:3], v[72:73] op_sel_hi:[0,1]
	v_pk_mul_f32 v[72:73], v[2:3], v[70:71] op_sel_hi:[0,1]
	ds_read_b128 v[86:89], v230 offset:384
	v_pk_mul_f32 v[70:71], v[2:3], v[74:75] op_sel_hi:[0,1]
	v_cvt_pk_bf16_f32 v68, v68, v69
	v_cvt_pk_bf16_f32 v69, v76, v77
	v_cvt_pk_bf16_f32 v70, v70, v71
	v_cvt_pk_bf16_f32 v71, v72, v73
	global_store_dwordx4 v[190:191], v[68:71], off
	s_waitcnt lgkmcnt(2)
	v_lshlrev_b32_e32 v72, 16, v90
	v_and_b32_e32 v73, 0xffff0000, v90
	v_lshlrev_b32_e32 v68, 16, v91
	v_and_b32_e32 v69, 0xffff0000, v91
	v_lshlrev_b32_e32 v74, 16, v92
	v_and_b32_e32 v75, 0xffff0000, v92
	v_lshlrev_b32_e32 v70, 16, v93
	v_and_b32_e32 v71, 0xffff0000, v93
	v_pk_mul_f32 v[76:77], v[2:3], v[68:69] op_sel_hi:[0,1]
	v_pk_mul_f32 v[68:69], v[2:3], v[72:73] op_sel_hi:[0,1]
	v_pk_mul_f32 v[72:73], v[2:3], v[70:71] op_sel_hi:[0,1]
	v_pk_mul_f32 v[70:71], v[2:3], v[74:75] op_sel_hi:[0,1]
	v_cvt_pk_bf16_f32 v68, v68, v69
	v_cvt_pk_bf16_f32 v69, v76, v77
	v_cvt_pk_bf16_f32 v70, v70, v71
	v_cvt_pk_bf16_f32 v71, v72, v73
	global_store_dwordx4 v[190:191], v[68:71], off offset:128
	s_waitcnt lgkmcnt(1)
	v_lshlrev_b32_e32 v72, 16, v94
	v_and_b32_e32 v73, 0xffff0000, v94
	v_lshlrev_b32_e32 v68, 16, v95
	v_and_b32_e32 v69, 0xffff0000, v95
	v_lshlrev_b32_e32 v74, 16, v96
	v_and_b32_e32 v75, 0xffff0000, v96
	v_lshlrev_b32_e32 v70, 16, v97
	v_and_b32_e32 v71, 0xffff0000, v97
	v_pk_mul_f32 v[76:77], v[2:3], v[68:69] op_sel_hi:[0,1]
	v_pk_mul_f32 v[68:69], v[2:3], v[72:73] op_sel_hi:[0,1]
	v_pk_mul_f32 v[72:73], v[2:3], v[70:71] op_sel_hi:[0,1]
	v_pk_mul_f32 v[70:71], v[2:3], v[74:75] op_sel_hi:[0,1]
	v_cvt_pk_bf16_f32 v68, v68, v69
	v_cvt_pk_bf16_f32 v69, v76, v77
	v_cvt_pk_bf16_f32 v70, v70, v71
	v_cvt_pk_bf16_f32 v71, v72, v73
	global_store_dwordx4 v[190:191], v[68:71], off offset:256
	s_waitcnt lgkmcnt(0)
	v_lshlrev_b32_e32 v72, 16, v86
	v_and_b32_e32 v73, 0xffff0000, v86
	v_lshlrev_b32_e32 v68, 16, v87
	v_and_b32_e32 v69, 0xffff0000, v87
	v_lshlrev_b32_e32 v74, 16, v88
	v_and_b32_e32 v75, 0xffff0000, v88
	v_lshlrev_b32_e32 v70, 16, v89
	v_and_b32_e32 v71, 0xffff0000, v89
	v_pk_mul_f32 v[76:77], v[2:3], v[68:69] op_sel_hi:[0,1]
	v_pk_mul_f32 v[68:69], v[2:3], v[72:73] op_sel_hi:[0,1]
	v_pk_mul_f32 v[72:73], v[2:3], v[70:71] op_sel_hi:[0,1]
	v_pk_mul_f32 v[2:3], v[2:3], v[74:75] op_sel_hi:[0,1]
	v_cvt_pk_bf16_f32 v68, v68, v69
	v_cvt_pk_bf16_f32 v69, v76, v77
	v_cvt_pk_bf16_f32 v70, v2, v3
	v_cvt_pk_bf16_f32 v71, v72, v73
	global_store_dwordx4 v[190:191], v[68:71], off offset:384
	s_cbranch_scc0 .LBB0_288
	s_mov_b32 s15, s14
	s_branch .LBB0_336
